# saddr2-carried-base
# speedup vs baseline: 1.0262x; 1.0038x over previous
; #define PG8_STAGE(bufoff, gbase, voff) do { _Pragma("unroll") for (int _i = 0; _i < 2; ++_i) \
;         __builtin_amdgcn_global_load_lds((const unsigned*)((const char*)(gbase) + (voff)[_i]), (LAS unsigned*)(lds + (bufoff) + ldsw + _i * 8192), 16, 0, 0); } while (0)
; #define PG8_LDA(dst, b, h) do { _Pragma("unroll") for (int m = 0; m < 4; ++m) _Pragma("unroll") for (int k = 0; k < 2; ++k) dst[m][k] = *(const LAS bf16x8*)(lds + PG8_SA(b, h) + aoff + m * 2048 + k * 1024); } while (0)
; #define PG8_LDB(dst, b, h) do { _Pragma("unroll") for (int n = 0; n < 2; ++n) _Pragma("unroll") for (int k = 0; k < 2; ++k) dst[n][k] = *(const LAS bf16x8*)(lds + PG8_SB(b, h) + boff + n * 2048 + k * 1024); } while (0)
; #define PG8_MMA(ai, bj, At, Bt) do { __builtin_amdgcn_s_setprio(1); _Pragma("unroll") for (int m = 0; m < 4; ++m) _Pragma("unroll") for (int n = 0; n < 2; ++n) _Pragma("unroll") for (int k = 0; k < 2; ++k) \
;         acc[ai][bj][m][n] = __builtin_amdgcn_mfma_f32_16x16x32_bf16(Bt[n][k], At[m][k], acc[ai][bj][m][n], 0, 0, 0); __builtin_amdgcn_s_setprio(0); } while (0)
; #define PG8_WAIT_V(n) asm volatile("s_waitcnt vmcnt(" #n ")" ::: "memory")
; #define PG8_WAIT_L(n) asm volatile("s_waitcnt lgkmcnt(" #n ")" ::: "memory")
; template <class Epi, class Sched, bool ATILE = false>
; __device__ __forceinline__ void gemm_phase(LAS unsigned char* lds, const Gemm g, const Sched& S, const Epi& E) {
;     ...
;         for (int t = 0; t < nt; t += 2) {
;             const bool last = (t == nt - 2);
;             const char* a1 = cA + (size_t)(t + 1) * kstepA;
;             const char* a2 = last ? nA : cA + (size_t)(t + 2) * kstepA; const char* b2 = last ? nB : cB + (size_t)(t + 2) * kstep;
;             const char* a3 = a2 + kstepA; const char* b3 = b2 + kstep;
;             PG8_LDB(B0, 0, 0); PG8_SCHED; PG8_LDA(At, 0, 0); PG8_STAGE(PG8_SA(1, 1), a1 + hstepA, voffA);
;             PG8_WAIT_L(8); PG8_BAR; PG8_WAIT_L(0); PG8_MMA(0, 0, At, B0); PG8_BAR; PG8_SCHED;
;             PG8_LDB(B1, 0, 1); PG8_STAGE(PG8_SB(0, 0), b2, voffB);
;             PG8_BAR; PG8_WAIT_L(0); PG8_MMA(0, 1, At, B1); PG8_BAR;
;             PG8_LDA(At, 0, 1); PG8_STAGE(PG8_SA(0, 0), a2, voffA);
;             PG8_BAR; PG8_WAIT_L(0); PG8_MMA(1, 0, At, B0); PG8_BAR; PG8_SCHED;
;             PG8_STAGE(PG8_SB(0, 1), b2 + hstepB, voffB);
;             PG8_WAIT_V(6); PG8_BAR; PG8_MMA(1, 1, At, B1); PG8_BAR;
.LBB0_625:
	ds_read_b128 v[182:185], v139
	ds_read_b128 v[186:189], v139 offset:1024
	ds_read_b128 v[190:193], v139 offset:2048
	ds_read_b128 v[194:197], v139 offset:3072
	s_add_i32 s62, s28, 2
	s_add_u32 s29, s26, 0xfff80080
	s_addc_u32 s30, s27, -1
	s_cmp_eq_u32 s59, s28
	s_cselect_b32 s28, s58, s60
	s_cselect_b32 s31, s13, s30
	s_cselect_b32 s30, s56, s29
	s_cselect_b32 s29, s57, s61
	s_add_i32 m0, s35, 0xc000
	ds_read_b128 v[198:201], v163
	ds_read_b128 v[202:205], v163 offset:1024
	ds_read_b128 v[206:209], v163 offset:2048
	ds_read_b128 v[210:213], v163 offset:3072
	ds_read_b128 v[214:217], v163 offset:4096
	ds_read_b128 v[218:221], v163 offset:5120
	ds_read_b128 v[222:225], v163 offset:6144
	ds_read_b128 v[226:229], v163 offset:7168
	global_load_lds_dwordx4 v172, s[26:27]
	s_add_i32 m0, s35, 0xe000
	s_nop 0
	global_load_lds_dwordx4 v174, s[26:27]
	s_waitcnt lgkmcnt(8)
	s_barrier
	s_waitcnt lgkmcnt(0)
	s_setprio 1
	s_waitcnt lgkmcnt(0)
	v_mfma_f32_16x16x32_bf16 v[120:123], v[182:185], v[198:201], v[120:123]
	v_mfma_f32_16x16x32_bf16 v[112:115], v[190:193], v[198:201], v[112:115]
	v_mfma_f32_16x16x32_bf16 v[104:107], v[182:185], v[206:209], v[104:107]
	v_mfma_f32_16x16x32_bf16 v[96:99], v[190:193], v[206:209], v[96:99]
	v_mfma_f32_16x16x32_bf16 v[88:91], v[182:185], v[214:217], v[88:91]
	v_mfma_f32_16x16x32_bf16 v[80:83], v[190:193], v[214:217], v[80:83]
	v_mfma_f32_16x16x32_bf16 v[72:75], v[182:185], v[222:225], v[72:75]
	v_mfma_f32_16x16x32_bf16 v[64:67], v[190:193], v[222:225], v[64:67]
	v_mfma_f32_16x16x32_bf16 v[120:123], v[186:189], v[202:205], v[120:123]
	v_mfma_f32_16x16x32_bf16 v[112:115], v[194:197], v[202:205], v[112:115]
	v_mfma_f32_16x16x32_bf16 v[104:107], v[186:189], v[210:213], v[104:107]
	v_mfma_f32_16x16x32_bf16 v[96:99], v[194:197], v[210:213], v[96:99]
	v_mfma_f32_16x16x32_bf16 v[88:91], v[186:189], v[218:221], v[88:91]
	v_mfma_f32_16x16x32_bf16 v[80:83], v[194:197], v[218:221], v[80:83]
	v_mfma_f32_16x16x32_bf16 v[72:75], v[186:189], v[226:229], v[72:75]
	v_mfma_f32_16x16x32_bf16 v[64:67], v[194:197], v[226:229], v[64:67]
	s_setprio 0
	s_barrier
	s_add_i32 s63, s53, s34
	s_add_u32 s98, s28, s0
	s_addc_u32 s99, s29, s1
	s_mov_b32 m0, s63
	ds_read_b128 v[230:233], v167
	ds_read_b128 v[234:237], v167 offset:1024
	ds_read_b128 v[238:241], v167 offset:2048
	ds_read_b128 v[242:245], v167 offset:3072
	global_load_lds_dwordx4 v130, s[28:29]
	s_add_i32 m0, s63, 0x2000
	s_nop 0
	global_load_lds_dwordx4 v134, s[28:29]
	s_barrier
	s_waitcnt lgkmcnt(0)
	s_setprio 1
	s_waitcnt lgkmcnt(0)
	v_mfma_f32_16x16x32_bf16 v[124:127], v[230:233], v[198:201], v[124:127]
	v_mfma_f32_16x16x32_bf16 v[116:119], v[238:241], v[198:201], v[116:119]
	v_mfma_f32_16x16x32_bf16 v[108:111], v[230:233], v[206:209], v[108:111]
	v_mfma_f32_16x16x32_bf16 v[100:103], v[238:241], v[206:209], v[100:103]
	v_mfma_f32_16x16x32_bf16 v[92:95], v[230:233], v[214:217], v[92:95]
	v_mfma_f32_16x16x32_bf16 v[84:87], v[238:241], v[214:217], v[84:87]
	v_mfma_f32_16x16x32_bf16 v[76:79], v[230:233], v[222:225], v[76:79]
	v_mfma_f32_16x16x32_bf16 v[68:71], v[238:241], v[222:225], v[68:71]
	v_mfma_f32_16x16x32_bf16 v[124:127], v[234:237], v[202:205], v[124:127]
	v_mfma_f32_16x16x32_bf16 v[116:119], v[242:245], v[202:205], v[116:119]
	v_mfma_f32_16x16x32_bf16 v[108:111], v[234:237], v[210:213], v[108:111]
	v_mfma_f32_16x16x32_bf16 v[100:103], v[242:245], v[210:213], v[100:103]
	v_mfma_f32_16x16x32_bf16 v[92:95], v[234:237], v[218:221], v[92:95]
	v_mfma_f32_16x16x32_bf16 v[84:87], v[242:245], v[218:221], v[84:87]
	v_mfma_f32_16x16x32_bf16 v[76:79], v[234:237], v[226:229], v[76:79]
	v_mfma_f32_16x16x32_bf16 v[68:71], v[242:245], v[226:229], v[68:71]
	s_setprio 0
	s_barrier
	s_mov_b32 m0, s35
	s_add_u32 s100, s30, s0
	s_addc_u32 s101, s31, s1
	ds_read_b128 v[198:201], v163 offset:16384
	ds_read_b128 v[202:205], v163 offset:17408
	ds_read_b128 v[206:209], v163 offset:18432
	ds_read_b128 v[210:213], v163 offset:19456
	ds_read_b128 v[214:217], v163 offset:20480
	ds_read_b128 v[218:221], v163 offset:21504
	ds_read_b128 v[222:225], v163 offset:22528
	ds_read_b128 v[226:229], v163 offset:23552
	global_load_lds_dwordx4 v128, s[30:31]
	s_mov_b32 m0, s36
	s_nop 0
	global_load_lds_dwordx4 v132, s[30:31]
	s_barrier
	s_waitcnt lgkmcnt(0)
	s_setprio 1
	s_waitcnt lgkmcnt(0)
	v_mfma_f32_16x16x32_bf16 v[56:59], v[182:185], v[198:201], v[56:59]
	v_mfma_f32_16x16x32_bf16 v[48:51], v[190:193], v[198:201], v[48:51]
	v_mfma_f32_16x16x32_bf16 v[40:43], v[182:185], v[206:209], v[40:43]
	v_mfma_f32_16x16x32_bf16 v[32:35], v[190:193], v[206:209], v[32:35]
	v_mfma_f32_16x16x32_bf16 v[24:27], v[182:185], v[214:217], v[24:27]
	v_mfma_f32_16x16x32_bf16 v[16:19], v[190:193], v[214:217], v[16:19]
	v_mfma_f32_16x16x32_bf16 v[8:11], v[182:185], v[222:225], v[8:11]
	v_mfma_f32_16x16x32_bf16 v[4:7], v[190:193], v[222:225], v[4:7]
	v_mfma_f32_16x16x32_bf16 v[56:59], v[186:189], v[202:205], v[56:59]
	v_mfma_f32_16x16x32_bf16 v[48:51], v[194:197], v[202:205], v[48:51]
	v_mfma_f32_16x16x32_bf16 v[40:43], v[186:189], v[210:213], v[40:43]
	v_mfma_f32_16x16x32_bf16 v[32:35], v[194:197], v[210:213], v[32:35]
	v_mfma_f32_16x16x32_bf16 v[24:27], v[186:189], v[218:221], v[24:27]
	v_mfma_f32_16x16x32_bf16 v[16:19], v[194:197], v[218:221], v[16:19]
	v_mfma_f32_16x16x32_bf16 v[8:11], v[186:189], v[226:229], v[8:11]
	v_mfma_f32_16x16x32_bf16 v[4:7], v[194:197], v[226:229], v[4:7]
	s_setprio 0
	s_barrier
	s_add_u32 s64, s28, 0x80000
	s_addc_u32 s65, s29, 0
	s_add_i32 s63, s54, s34
	s_mov_b32 m0, s63
	s_nop 0
	global_load_lds_dwordx4 v130, s[64:65]
	s_add_i32 m0, s63, 0x2000
	s_nop 0
	global_load_lds_dwordx4 v134, s[64:65]
	s_waitcnt vmcnt(6)
	s_barrier
; #define PG8_STAGE(bufoff, gbase, voff) do { _Pragma("unroll") for (int _i = 0; _i < 2; ++_i) \
;         __builtin_amdgcn_global_load_lds((const unsigned*)((const char*)(gbase) + (voff)[_i]), (LAS unsigned*)(lds + (bufoff) + ldsw + _i * 8192), 16, 0, 0); } while (0)
; #define PG8_LDA(dst, b, h) do { _Pragma("unroll") for (int m = 0; m < 4; ++m) _Pragma("unroll") for (int k = 0; k < 2; ++k) dst[m][k] = *(const LAS bf16x8*)(lds + PG8_SA(b, h) + aoff + m * 2048 + k * 1024); } while (0)
; #define PG8_LDB(dst, b, h) do { _Pragma("unroll") for (int n = 0; n < 2; ++n) _Pragma("unroll") for (int k = 0; k < 2; ++k) dst[n][k] = *(const LAS bf16x8*)(lds + PG8_SB(b, h) + boff + n * 2048 + k * 1024); } while (0)
; #define PG8_MMA(ai, bj, At, Bt) do { __builtin_amdgcn_s_setprio(1); _Pragma("unroll") for (int m = 0; m < 4; ++m) _Pragma("unroll") for (int n = 0; n < 2; ++n) _Pragma("unroll") for (int k = 0; k < 2; ++k) \
;         acc[ai][bj][m][n] = __builtin_amdgcn_mfma_f32_16x16x32_bf16(Bt[n][k], At[m][k], acc[ai][bj][m][n], 0, 0, 0); __builtin_amdgcn_s_setprio(0); } while (0)
; #define PG8_WAIT_V(n) asm volatile("s_waitcnt vmcnt(" #n ")" ::: "memory")
; #define PG8_WAIT_L(n) asm volatile("s_waitcnt lgkmcnt(" #n ")" ::: "memory")
; #define PG8_BAR __builtin_amdgcn_s_barrier()
; #define PG8_SCHED __builtin_amdgcn_sched_barrier(0)
; template <class Epi, class Sched, bool ATILE = false>
; __device__ __forceinline__ void gemm_phase(LAS unsigned char* lds, const Gemm g, const Sched& S, const Epi& E) {
;     ...
;             PG8_WAIT_V(6); PG8_BAR; PG8_MMA(1, 1, At, B1); PG8_BAR;
;             PG8_LDB(B0, 1, 0); PG8_SCHED; PG8_LDA(At, 1, 0); PG8_STAGE(PG8_SA(0, 1), a2 + hstepA, voffA);
;             PG8_WAIT_L(8); PG8_BAR; PG8_WAIT_L(0); PG8_MMA(0, 0, At, B0); PG8_BAR; PG8_SCHED;
;             PG8_LDB(B1, 1, 1); PG8_STAGE(PG8_SB(1, 0), b3, voffB);
;             PG8_BAR; PG8_WAIT_L(0); PG8_MMA(0, 1, At, B1); PG8_BAR;
	s_setprio 1
	v_mfma_f32_16x16x32_bf16 v[60:63], v[230:233], v[198:201], v[60:63]
	v_mfma_f32_16x16x32_bf16 v[52:55], v[238:241], v[198:201], v[52:55]
	v_mfma_f32_16x16x32_bf16 v[44:47], v[230:233], v[206:209], v[44:47]
	v_mfma_f32_16x16x32_bf16 v[36:39], v[238:241], v[206:209], v[36:39]
	v_mfma_f32_16x16x32_bf16 v[28:31], v[230:233], v[214:217], v[28:31]
	v_mfma_f32_16x16x32_bf16 v[20:23], v[238:241], v[214:217], v[20:23]
	v_mfma_f32_16x16x32_bf16 v[12:15], v[230:233], v[222:225], v[12:15]
	v_mfma_f32_16x16x32_bf16 v[0:3], v[238:241], v[222:225], v[0:3]
	v_mfma_f32_16x16x32_bf16 v[60:63], v[234:237], v[202:205], v[60:63]
	v_mfma_f32_16x16x32_bf16 v[52:55], v[242:245], v[202:205], v[52:55]
	v_mfma_f32_16x16x32_bf16 v[44:47], v[234:237], v[210:213], v[44:47]
	v_mfma_f32_16x16x32_bf16 v[36:39], v[242:245], v[210:213], v[36:39]
	v_mfma_f32_16x16x32_bf16 v[28:31], v[234:237], v[218:221], v[28:31]
	v_mfma_f32_16x16x32_bf16 v[20:23], v[242:245], v[218:221], v[20:23]
	v_mfma_f32_16x16x32_bf16 v[12:15], v[234:237], v[226:229], v[12:15]
	v_mfma_f32_16x16x32_bf16 v[0:3], v[242:245], v[226:229], v[0:3]
	s_setprio 0
	s_barrier
	s_add_i32 s63, 0, 0x18000
	v_add_u32_e32 v176, s63, v161
	ds_read_b128 v[182:185], v176
	ds_read_b128 v[186:189], v176 offset:1024
	ds_read_b128 v[190:193], v176 offset:2048
	ds_read_b128 v[194:197], v176 offset:3072
	s_add_u32 s30, s30, 0x80000
	s_addc_u32 s31, s31, 0
	s_mov_b32 m0, s37
	ds_read_b128 v[198:201], v163 offset:32768
	ds_read_b128 v[202:205], v163 offset:33792
	ds_read_b128 v[206:209], v163 offset:34816
	ds_read_b128 v[210:213], v163 offset:35840
	ds_read_b128 v[214:217], v163 offset:36864
	ds_read_b128 v[218:221], v163 offset:37888
	ds_read_b128 v[222:225], v163 offset:38912
	ds_read_b128 v[226:229], v163 offset:39936
	global_load_lds_dwordx4 v128, s[30:31]
	s_mov_b32 m0, s38
	s_nop 0
	global_load_lds_dwordx4 v132, s[30:31]
	s_waitcnt lgkmcnt(8)
	s_barrier
	s_waitcnt lgkmcnt(0)
	s_setprio 1
	s_waitcnt lgkmcnt(0)
	v_mfma_f32_16x16x32_bf16 v[120:123], v[182:185], v[198:201], v[120:123]
	v_mfma_f32_16x16x32_bf16 v[112:115], v[190:193], v[198:201], v[112:115]
	v_mfma_f32_16x16x32_bf16 v[104:107], v[182:185], v[206:209], v[104:107]
	v_mfma_f32_16x16x32_bf16 v[96:99], v[190:193], v[206:209], v[96:99]
	v_mfma_f32_16x16x32_bf16 v[88:91], v[182:185], v[214:217], v[88:91]
	v_mfma_f32_16x16x32_bf16 v[80:83], v[190:193], v[214:217], v[80:83]
	v_mfma_f32_16x16x32_bf16 v[72:75], v[182:185], v[222:225], v[72:75]
	v_mfma_f32_16x16x32_bf16 v[64:67], v[190:193], v[222:225], v[64:67]
	v_mfma_f32_16x16x32_bf16 v[120:123], v[186:189], v[202:205], v[120:123]
	v_mfma_f32_16x16x32_bf16 v[112:115], v[194:197], v[202:205], v[112:115]
	v_mfma_f32_16x16x32_bf16 v[104:107], v[186:189], v[210:213], v[104:107]
	v_mfma_f32_16x16x32_bf16 v[96:99], v[194:197], v[210:213], v[96:99]
	v_mfma_f32_16x16x32_bf16 v[88:91], v[186:189], v[218:221], v[88:91]
	v_mfma_f32_16x16x32_bf16 v[80:83], v[194:197], v[218:221], v[80:83]
	v_mfma_f32_16x16x32_bf16 v[72:75], v[186:189], v[226:229], v[72:75]
	v_mfma_f32_16x16x32_bf16 v[64:67], v[194:197], v[226:229], v[64:67]
	s_setprio 0
	s_barrier
	s_add_i32 s30, 0, 0x1c000
	s_add_i32 s31, s63, s34
	v_add_u32_e32 v176, s30, v161
	s_mov_b32 m0, s31
	ds_read_b128 v[230:233], v176
	ds_read_b128 v[234:237], v176 offset:1024
	ds_read_b128 v[238:241], v176 offset:2048
	ds_read_b128 v[242:245], v176 offset:3072
	global_load_lds_dwordx4 v130, s[98:99]
	s_add_i32 m0, s31, 0x2000
	s_nop 0
	global_load_lds_dwordx4 v134, s[98:99]
	s_barrier
; #define PG8_STAGE(bufoff, gbase, voff) do { _Pragma("unroll") for (int _i = 0; _i < 2; ++_i) \
;         __builtin_amdgcn_global_load_lds((const unsigned*)((const char*)(gbase) + (voff)[_i]), (LAS unsigned*)(lds + (bufoff) + ldsw + _i * 8192), 16, 0, 0); } while (0)
; #define PG8_LDA(dst, b, h) do { _Pragma("unroll") for (int m = 0; m < 4; ++m) _Pragma("unroll") for (int k = 0; k < 2; ++k) dst[m][k] = *(const LAS bf16x8*)(lds + PG8_SA(b, h) + aoff + m * 2048 + k * 1024); } while (0)
; #define PG8_MMA(ai, bj, At, Bt) do { __builtin_amdgcn_s_setprio(1); _Pragma("unroll") for (int m = 0; m < 4; ++m) _Pragma("unroll") for (int n = 0; n < 2; ++n) _Pragma("unroll") for (int k = 0; k < 2; ++k) \
;         acc[ai][bj][m][n] = __builtin_amdgcn_mfma_f32_16x16x32_bf16(Bt[n][k], At[m][k], acc[ai][bj][m][n], 0, 0, 0); __builtin_amdgcn_s_setprio(0); } while (0)
; #define PG8_WAIT_V(n) asm volatile("s_waitcnt vmcnt(" #n ")" ::: "memory")
; #define PG8_WAIT_L(n) asm volatile("s_waitcnt lgkmcnt(" #n ")" ::: "memory")
; #define PG8_BAR __builtin_amdgcn_s_barrier()
; #define PG8_SCHED __builtin_amdgcn_sched_barrier(0)
; template <class Epi, class Sched, bool ATILE = false>
; __device__ __forceinline__ void gemm_phase(LAS unsigned char* lds, const Gemm g, const Sched& S, const Epi& E) {
;     ...
;             PG8_BAR; PG8_WAIT_L(0); PG8_MMA(0, 1, At, B1); PG8_BAR;
;             PG8_LDA(At, 1, 1); PG8_STAGE(PG8_SA(1, 0), a3, voffA);
;             PG8_BAR; PG8_WAIT_L(0); PG8_MMA(1, 0, At, B0); PG8_BAR; PG8_SCHED;
;             PG8_STAGE(PG8_SB(1, 1), b3 + hstepB, voffB);
;             PG8_WAIT_V(6); PG8_BAR; PG8_MMA(1, 1, At, B1); PG8_BAR;
;         }
;         E(acc, cur, wr, wc, fr, fq);
;         if (!has_next) break;
	s_waitcnt lgkmcnt(0)
	s_setprio 1
	s_waitcnt lgkmcnt(0)
	v_mfma_f32_16x16x32_bf16 v[124:127], v[230:233], v[198:201], v[124:127]
	v_mfma_f32_16x16x32_bf16 v[116:119], v[238:241], v[198:201], v[116:119]
	v_mfma_f32_16x16x32_bf16 v[108:111], v[230:233], v[206:209], v[108:111]
	v_mfma_f32_16x16x32_bf16 v[100:103], v[238:241], v[206:209], v[100:103]
	v_mfma_f32_16x16x32_bf16 v[92:95], v[230:233], v[214:217], v[92:95]
	v_mfma_f32_16x16x32_bf16 v[84:87], v[238:241], v[214:217], v[84:87]
	v_mfma_f32_16x16x32_bf16 v[76:79], v[230:233], v[222:225], v[76:79]
	v_mfma_f32_16x16x32_bf16 v[68:71], v[238:241], v[222:225], v[68:71]
	v_mfma_f32_16x16x32_bf16 v[124:127], v[234:237], v[202:205], v[124:127]
	v_mfma_f32_16x16x32_bf16 v[116:119], v[242:245], v[202:205], v[116:119]
	v_mfma_f32_16x16x32_bf16 v[108:111], v[234:237], v[210:213], v[108:111]
	v_mfma_f32_16x16x32_bf16 v[100:103], v[242:245], v[210:213], v[100:103]
	v_mfma_f32_16x16x32_bf16 v[92:95], v[234:237], v[218:221], v[92:95]
	v_mfma_f32_16x16x32_bf16 v[84:87], v[242:245], v[218:221], v[84:87]
	v_mfma_f32_16x16x32_bf16 v[76:79], v[234:237], v[226:229], v[76:79]
	v_mfma_f32_16x16x32_bf16 v[68:71], v[242:245], v[226:229], v[68:71]
	s_setprio 0
	s_barrier
	s_mov_b32 m0, s41
	ds_read_b128 v[198:201], v163 offset:49152
	ds_read_b128 v[202:205], v163 offset:50176
	ds_read_b128 v[206:209], v163 offset:51200
	ds_read_b128 v[210:213], v163 offset:52224
	ds_read_b128 v[214:217], v163 offset:53248
	ds_read_b128 v[218:221], v163 offset:54272
	ds_read_b128 v[222:225], v163 offset:55296
	ds_read_b128 v[226:229], v163 offset:56320
	global_load_lds_dwordx4 v128, s[100:101]
	s_mov_b32 m0, s42
	s_nop 0
	global_load_lds_dwordx4 v132, s[100:101]
	s_barrier
	s_waitcnt lgkmcnt(0)
	s_setprio 1
	s_waitcnt lgkmcnt(0)
	v_mfma_f32_16x16x32_bf16 v[56:59], v[182:185], v[198:201], v[56:59]
	v_mfma_f32_16x16x32_bf16 v[48:51], v[190:193], v[198:201], v[48:51]
	v_mfma_f32_16x16x32_bf16 v[40:43], v[182:185], v[206:209], v[40:43]
	v_mfma_f32_16x16x32_bf16 v[32:35], v[190:193], v[206:209], v[32:35]
	v_mfma_f32_16x16x32_bf16 v[24:27], v[182:185], v[214:217], v[24:27]
	v_mfma_f32_16x16x32_bf16 v[16:19], v[190:193], v[214:217], v[16:19]
	v_mfma_f32_16x16x32_bf16 v[8:11], v[182:185], v[222:225], v[8:11]
	v_mfma_f32_16x16x32_bf16 v[4:7], v[190:193], v[222:225], v[4:7]
	v_mfma_f32_16x16x32_bf16 v[56:59], v[186:189], v[202:205], v[56:59]
	v_mfma_f32_16x16x32_bf16 v[48:51], v[194:197], v[202:205], v[48:51]
	v_mfma_f32_16x16x32_bf16 v[40:43], v[186:189], v[210:213], v[40:43]
	v_mfma_f32_16x16x32_bf16 v[32:35], v[194:197], v[210:213], v[32:35]
	v_mfma_f32_16x16x32_bf16 v[24:27], v[186:189], v[218:221], v[24:27]
	v_mfma_f32_16x16x32_bf16 v[16:19], v[194:197], v[218:221], v[16:19]
	v_mfma_f32_16x16x32_bf16 v[8:11], v[186:189], v[226:229], v[8:11]
	v_mfma_f32_16x16x32_bf16 v[4:7], v[194:197], v[226:229], v[4:7]
	s_setprio 0
	s_barrier
	s_add_u32 s28, s28, 0x80080
	s_addc_u32 s29, s29, 0
	s_add_i32 s30, s30, s34
	s_mov_b32 m0, s30
	s_nop 0
	global_load_lds_dwordx4 v130, s[28:29]
	s_add_i32 m0, s30, 0x2000
	s_nop 0
	global_load_lds_dwordx4 v134, s[28:29]
	s_waitcnt vmcnt(6)
	s_barrier
	s_setprio 1
	v_mfma_f32_16x16x32_bf16 v[60:63], v[230:233], v[198:201], v[60:63]
	v_mfma_f32_16x16x32_bf16 v[52:55], v[238:241], v[198:201], v[52:55]
	v_mfma_f32_16x16x32_bf16 v[44:47], v[230:233], v[206:209], v[44:47]
	v_mfma_f32_16x16x32_bf16 v[36:39], v[238:241], v[206:209], v[36:39]
	v_mfma_f32_16x16x32_bf16 v[28:31], v[230:233], v[214:217], v[28:31]
	v_mfma_f32_16x16x32_bf16 v[20:23], v[238:241], v[214:217], v[20:23]
	v_mfma_f32_16x16x32_bf16 v[12:15], v[230:233], v[222:225], v[12:15]
	v_mfma_f32_16x16x32_bf16 v[0:3], v[238:241], v[222:225], v[0:3]
	v_mfma_f32_16x16x32_bf16 v[60:63], v[234:237], v[202:205], v[60:63]
	v_mfma_f32_16x16x32_bf16 v[52:55], v[242:245], v[202:205], v[52:55]
	v_mfma_f32_16x16x32_bf16 v[44:47], v[234:237], v[210:213], v[44:47]
	v_mfma_f32_16x16x32_bf16 v[36:39], v[242:245], v[210:213], v[36:39]
	v_mfma_f32_16x16x32_bf16 v[28:31], v[234:237], v[218:221], v[28:31]
	v_mfma_f32_16x16x32_bf16 v[20:23], v[242:245], v[218:221], v[20:23]
	v_mfma_f32_16x16x32_bf16 v[12:15], v[234:237], v[226:229], v[12:15]
	v_mfma_f32_16x16x32_bf16 v[0:3], v[242:245], v[226:229], v[0:3]
	s_setprio 0
	s_barrier
	s_add_u32 s26, s26, 0x100
	s_addc_u32 s27, s27, 0
	s_add_u32 s60, s60, 0x100
	s_addc_u32 s61, s61, 0
	s_cmp_ge_i32 s62, s11
	s_mov_b32 s28, s62
	s_cbranch_scc0 .LBB0_625
	s_branch .LBB0_616

; #define PG8_STAGE(bufoff, gbase, voff) do { _Pragma("unroll") for (int _i = 0; _i < 2; ++_i) \
;         __builtin_amdgcn_global_load_lds((const unsigned*)((const char*)(gbase) + (voff)[_i]), (LAS unsigned*)(lds + (bufoff) + ldsw + _i * 8192), 16, 0, 0); } while (0)
; #define PG8_LDA(dst, b, h) do { _Pragma("unroll") for (int m = 0; m < 4; ++m) _Pragma("unroll") for (int k = 0; k < 2; ++k) dst[m][k] = *(const LAS bf16x8*)(lds + PG8_SA(b, h) + aoff + m * 2048 + k * 1024); } while (0)
; #define PG8_LDB(dst, b, h) do { _Pragma("unroll") for (int n = 0; n < 2; ++n) _Pragma("unroll") for (int k = 0; k < 2; ++k) dst[n][k] = *(const LAS bf16x8*)(lds + PG8_SB(b, h) + boff + n * 2048 + k * 1024); } while (0)
; #define PG8_MMA(ai, bj, At, Bt) do { __builtin_amdgcn_s_setprio(1); _Pragma("unroll") for (int m = 0; m < 4; ++m) _Pragma("unroll") for (int n = 0; n < 2; ++n) _Pragma("unroll") for (int k = 0; k < 2; ++k) \
;         acc[ai][bj][m][n] = __builtin_amdgcn_mfma_f32_16x16x32_bf16(Bt[n][k], At[m][k], acc[ai][bj][m][n], 0, 0, 0); __builtin_amdgcn_s_setprio(0); } while (0)
; #define PG8_WAIT_V(n) asm volatile("s_waitcnt vmcnt(" #n ")" ::: "memory")
; #define PG8_WAIT_L(n) asm volatile("s_waitcnt lgkmcnt(" #n ")" ::: "memory")
; template <class Epi, class Sched, bool ATILE = false>
; __device__ __forceinline__ void gemm_phase(LAS unsigned char* lds, const Gemm g, const Sched& S, const Epi& E) {
;     ...
;         for (int t = 0; t < nt; t += 2) {
;             const bool last = (t == nt - 2);
;             const char* a1 = cA + (size_t)(t + 1) * kstepA;
;             const char* a2 = last ? nA : cA + (size_t)(t + 2) * kstepA; const char* b2 = last ? nB : cB + (size_t)(t + 2) * kstep;
;             const char* a3 = a2 + kstepA; const char* b3 = b2 + kstep;
;             PG8_LDB(B0, 0, 0); PG8_SCHED; PG8_LDA(At, 0, 0); PG8_STAGE(PG8_SA(1, 1), a1 + hstepA, voffA);
;             PG8_WAIT_L(8); PG8_BAR; PG8_WAIT_L(0); PG8_MMA(0, 0, At, B0); PG8_BAR; PG8_SCHED;
;             PG8_LDB(B1, 0, 1); PG8_STAGE(PG8_SB(0, 0), b2, voffB);
;             PG8_BAR; PG8_WAIT_L(0); PG8_MMA(0, 1, At, B1); PG8_BAR;
;             PG8_LDA(At, 0, 1); PG8_STAGE(PG8_SA(0, 0), a2, voffA);
;             PG8_BAR; PG8_WAIT_L(0); PG8_MMA(1, 0, At, B0); PG8_BAR; PG8_SCHED;
;             PG8_STAGE(PG8_SB(0, 1), b2 + hstepB, voffB);
;             PG8_WAIT_V(6); PG8_BAR; PG8_MMA(1, 1, At, B1); PG8_BAR;
.LBB0_1517:
	ds_read_b128 v[96:99], v182
	ds_read_b128 v[100:103], v182 offset:1024
	ds_read_b128 v[112:115], v182 offset:2048
	ds_read_b128 v[116:119], v182 offset:3072
	s_add_i32 s54, s26, 2
	s_add_u32 s27, s24, 0xfffc0080
	s_addc_u32 s28, s25, -1
	s_cmp_eq_u32 s45, s26
	s_cselect_b32 s26, s44, s52
	s_cselect_b32 s29, s17, s28
	s_cselect_b32 s28, s42, s27
	s_cselect_b32 s27, s43, s53
	s_add_i32 m0, s23, 0xc000
	ds_read_b128 v[144:147], v183
	ds_read_b128 v[174:177], v183 offset:1024
	ds_read_b128 v[178:181], v183 offset:2048
	ds_read_b128 v[186:189], v183 offset:3072
	ds_read_b128 v[190:193], v183 offset:4096
	ds_read_b128 v[194:197], v183 offset:5120
	ds_read_b128 v[198:201], v183 offset:6144
	ds_read_b128 v[202:205], v183 offset:7168
	global_load_lds_dwordx4 v166, s[24:25]
	s_add_i32 m0, s23, 0xe000
	s_nop 0
	global_load_lds_dwordx4 v168, s[24:25]
	s_waitcnt lgkmcnt(8)
	s_barrier
	s_waitcnt lgkmcnt(0)
	s_setprio 1
	s_waitcnt lgkmcnt(0)
	v_mfma_f32_16x16x32_bf16 v[140:143], v[96:99], v[144:147], v[140:143]
	v_mfma_f32_16x16x32_bf16 v[136:139], v[112:115], v[144:147], v[136:139]
	v_mfma_f32_16x16x32_bf16 v[124:127], v[96:99], v[178:181], v[124:127]
	v_mfma_f32_16x16x32_bf16 v[120:123], v[112:115], v[178:181], v[120:123]
	v_mfma_f32_16x16x32_bf16 v[92:95], v[96:99], v[190:193], v[92:95]
	v_mfma_f32_16x16x32_bf16 v[88:91], v[112:115], v[190:193], v[88:91]
	v_mfma_f32_16x16x32_bf16 v[76:79], v[96:99], v[198:201], v[76:79]
	v_mfma_f32_16x16x32_bf16 v[72:75], v[112:115], v[198:201], v[72:75]
	v_mfma_f32_16x16x32_bf16 v[140:143], v[100:103], v[174:177], v[140:143]
	v_mfma_f32_16x16x32_bf16 v[136:139], v[116:119], v[174:177], v[136:139]
	v_mfma_f32_16x16x32_bf16 v[124:127], v[100:103], v[186:189], v[124:127]
	v_mfma_f32_16x16x32_bf16 v[120:123], v[116:119], v[186:189], v[120:123]
	v_mfma_f32_16x16x32_bf16 v[92:95], v[100:103], v[194:197], v[92:95]
	v_mfma_f32_16x16x32_bf16 v[88:91], v[116:119], v[194:197], v[88:91]
	v_mfma_f32_16x16x32_bf16 v[76:79], v[100:103], v[202:205], v[76:79]
	v_mfma_f32_16x16x32_bf16 v[72:75], v[116:119], v[202:205], v[72:75]
	s_setprio 0
	s_barrier
	s_add_i32 s55, s39, s5
	s_add_u32 s98, s26, s10
	s_addc_u32 s99, s27, s11
	s_mov_b32 m0, s55
	ds_read_b128 v[206:209], v184
	ds_read_b128 v[210:213], v184 offset:1024
	ds_read_b128 v[214:217], v184 offset:2048
	ds_read_b128 v[218:221], v184 offset:3072
	global_load_lds_dwordx4 v150, s[26:27]
	s_add_i32 m0, s55, 0x2000
	s_nop 0
	global_load_lds_dwordx4 v164, s[26:27]
	s_barrier
	s_waitcnt lgkmcnt(0)
	s_setprio 1
	s_waitcnt lgkmcnt(0)
	v_mfma_f32_16x16x32_bf16 v[132:135], v[206:209], v[144:147], v[132:135]
	v_mfma_f32_16x16x32_bf16 v[128:131], v[214:217], v[144:147], v[128:131]
	v_mfma_f32_16x16x32_bf16 v[108:111], v[206:209], v[178:181], v[108:111]
	v_mfma_f32_16x16x32_bf16 v[104:107], v[214:217], v[178:181], v[104:107]
	v_mfma_f32_16x16x32_bf16 v[84:87], v[206:209], v[190:193], v[84:87]
	v_mfma_f32_16x16x32_bf16 v[80:83], v[214:217], v[190:193], v[80:83]
	v_mfma_f32_16x16x32_bf16 v[68:71], v[206:209], v[198:201], v[68:71]
	v_mfma_f32_16x16x32_bf16 v[64:67], v[214:217], v[198:201], v[64:67]
	v_mfma_f32_16x16x32_bf16 v[132:135], v[210:213], v[174:177], v[132:135]
	v_mfma_f32_16x16x32_bf16 v[128:131], v[218:221], v[174:177], v[128:131]
	v_mfma_f32_16x16x32_bf16 v[108:111], v[210:213], v[186:189], v[108:111]
	v_mfma_f32_16x16x32_bf16 v[104:107], v[218:221], v[186:189], v[104:107]
	v_mfma_f32_16x16x32_bf16 v[84:87], v[210:213], v[194:197], v[84:87]
	v_mfma_f32_16x16x32_bf16 v[80:83], v[218:221], v[194:197], v[80:83]
	v_mfma_f32_16x16x32_bf16 v[68:71], v[210:213], v[202:205], v[68:71]
	v_mfma_f32_16x16x32_bf16 v[64:67], v[218:221], v[202:205], v[64:67]
	s_setprio 0
	s_barrier
	s_mov_b32 m0, s23
	s_add_u32 s100, s28, s10
	s_addc_u32 s101, s29, s11
	ds_read_b128 v[144:147], v183 offset:16384
	ds_read_b128 v[174:177], v183 offset:17408
	ds_read_b128 v[178:181], v183 offset:18432
	ds_read_b128 v[186:189], v183 offset:19456
	ds_read_b128 v[190:193], v183 offset:20480
	ds_read_b128 v[194:197], v183 offset:21504
	ds_read_b128 v[198:201], v183 offset:22528
	ds_read_b128 v[202:205], v183 offset:23552
	global_load_lds_dwordx4 v148, s[28:29]
	s_mov_b32 m0, s30
	s_nop 0
	global_load_lds_dwordx4 v162, s[28:29]
	s_barrier
	s_waitcnt lgkmcnt(0)
	s_setprio 1
	s_waitcnt lgkmcnt(0)
	v_mfma_f32_16x16x32_bf16 v[60:63], v[96:99], v[144:147], v[60:63]
	v_mfma_f32_16x16x32_bf16 v[56:59], v[112:115], v[144:147], v[56:59]
	v_mfma_f32_16x16x32_bf16 v[44:47], v[96:99], v[178:181], v[44:47]
	v_mfma_f32_16x16x32_bf16 v[40:43], v[112:115], v[178:181], v[40:43]
	v_mfma_f32_16x16x32_bf16 v[28:31], v[96:99], v[190:193], v[28:31]
	v_mfma_f32_16x16x32_bf16 v[24:27], v[112:115], v[190:193], v[24:27]
	v_mfma_f32_16x16x32_bf16 v[12:15], v[96:99], v[198:201], v[12:15]
	v_mfma_f32_16x16x32_bf16 v[8:11], v[112:115], v[198:201], v[8:11]
	v_mfma_f32_16x16x32_bf16 v[60:63], v[100:103], v[174:177], v[60:63]
	v_mfma_f32_16x16x32_bf16 v[56:59], v[116:119], v[174:177], v[56:59]
	v_mfma_f32_16x16x32_bf16 v[44:47], v[100:103], v[186:189], v[44:47]
	v_mfma_f32_16x16x32_bf16 v[40:43], v[116:119], v[186:189], v[40:43]
	v_mfma_f32_16x16x32_bf16 v[28:31], v[100:103], v[194:197], v[28:31]
	v_mfma_f32_16x16x32_bf16 v[24:27], v[116:119], v[194:197], v[24:27]
	v_mfma_f32_16x16x32_bf16 v[12:15], v[100:103], v[202:205], v[12:15]
	v_mfma_f32_16x16x32_bf16 v[8:11], v[116:119], v[202:205], v[8:11]
	s_setprio 0
	s_barrier
	s_add_u32 s56, s26, 0x40000
	s_addc_u32 s57, s27, 0
	s_add_i32 s55, s40, s5
	s_mov_b32 m0, s55
	s_nop 0
	global_load_lds_dwordx4 v150, s[56:57]
	s_add_i32 m0, s55, 0x2000
	s_nop 0
	global_load_lds_dwordx4 v164, s[56:57]
	s_waitcnt vmcnt(6)
	s_barrier
; #define PG8_STAGE(bufoff, gbase, voff) do { _Pragma("unroll") for (int _i = 0; _i < 2; ++_i) \
;         __builtin_amdgcn_global_load_lds((const unsigned*)((const char*)(gbase) + (voff)[_i]), (LAS unsigned*)(lds + (bufoff) + ldsw + _i * 8192), 16, 0, 0); } while (0)
; #define PG8_LDA(dst, b, h) do { _Pragma("unroll") for (int m = 0; m < 4; ++m) _Pragma("unroll") for (int k = 0; k < 2; ++k) dst[m][k] = *(const LAS bf16x8*)(lds + PG8_SA(b, h) + aoff + m * 2048 + k * 1024); } while (0)
; #define PG8_LDB(dst, b, h) do { _Pragma("unroll") for (int n = 0; n < 2; ++n) _Pragma("unroll") for (int k = 0; k < 2; ++k) dst[n][k] = *(const LAS bf16x8*)(lds + PG8_SB(b, h) + boff + n * 2048 + k * 1024); } while (0)
; #define PG8_MMA(ai, bj, At, Bt) do { __builtin_amdgcn_s_setprio(1); _Pragma("unroll") for (int m = 0; m < 4; ++m) _Pragma("unroll") for (int n = 0; n < 2; ++n) _Pragma("unroll") for (int k = 0; k < 2; ++k) \
;         acc[ai][bj][m][n] = __builtin_amdgcn_mfma_f32_16x16x32_bf16(Bt[n][k], At[m][k], acc[ai][bj][m][n], 0, 0, 0); __builtin_amdgcn_s_setprio(0); } while (0)
; #define PG8_WAIT_V(n) asm volatile("s_waitcnt vmcnt(" #n ")" ::: "memory")
; #define PG8_WAIT_L(n) asm volatile("s_waitcnt lgkmcnt(" #n ")" ::: "memory")
; #define PG8_BAR __builtin_amdgcn_s_barrier()
; #define PG8_SCHED __builtin_amdgcn_sched_barrier(0)
; template <class Epi, class Sched, bool ATILE = false>
; __device__ __forceinline__ void gemm_phase(LAS unsigned char* lds, const Gemm g, const Sched& S, const Epi& E) {
;     ...
;             PG8_WAIT_V(6); PG8_BAR; PG8_MMA(1, 1, At, B1); PG8_BAR;
;             PG8_LDB(B0, 1, 0); PG8_SCHED; PG8_LDA(At, 1, 0); PG8_STAGE(PG8_SA(0, 1), a2 + hstepA, voffA);
;             PG8_WAIT_L(8); PG8_BAR; PG8_WAIT_L(0); PG8_MMA(0, 0, At, B0); PG8_BAR; PG8_SCHED;
;             PG8_LDB(B1, 1, 1); PG8_STAGE(PG8_SB(1, 0), b3, voffB);
;             PG8_BAR; PG8_WAIT_L(0); PG8_MMA(0, 1, At, B1); PG8_BAR;
	s_setprio 1
	v_mfma_f32_16x16x32_bf16 v[52:55], v[206:209], v[144:147], v[52:55]
	v_mfma_f32_16x16x32_bf16 v[48:51], v[214:217], v[144:147], v[48:51]
	v_mfma_f32_16x16x32_bf16 v[36:39], v[206:209], v[178:181], v[36:39]
	v_mfma_f32_16x16x32_bf16 v[32:35], v[214:217], v[178:181], v[32:35]
	v_mfma_f32_16x16x32_bf16 v[20:23], v[206:209], v[190:193], v[20:23]
	v_mfma_f32_16x16x32_bf16 v[16:19], v[214:217], v[190:193], v[16:19]
	v_mfma_f32_16x16x32_bf16 v[4:7], v[206:209], v[198:201], v[4:7]
	v_mfma_f32_16x16x32_bf16 v[0:3], v[214:217], v[198:201], v[0:3]
	v_mfma_f32_16x16x32_bf16 v[52:55], v[210:213], v[174:177], v[52:55]
	v_mfma_f32_16x16x32_bf16 v[48:51], v[218:221], v[174:177], v[48:51]
	v_mfma_f32_16x16x32_bf16 v[36:39], v[210:213], v[186:189], v[36:39]
	v_mfma_f32_16x16x32_bf16 v[32:35], v[218:221], v[186:189], v[32:35]
	v_mfma_f32_16x16x32_bf16 v[20:23], v[210:213], v[194:197], v[20:23]
	v_mfma_f32_16x16x32_bf16 v[16:19], v[218:221], v[194:197], v[16:19]
	v_mfma_f32_16x16x32_bf16 v[4:7], v[210:213], v[202:205], v[4:7]
	v_mfma_f32_16x16x32_bf16 v[0:3], v[218:221], v[202:205], v[0:3]
	s_setprio 0
	s_barrier
	s_add_i32 s55, 0, 0x18000
	v_add_u32_e32 v116, s55, v159
	ds_read_b128 v[96:99], v116
	ds_read_b128 v[100:103], v116 offset:1024
	ds_read_b128 v[112:115], v116 offset:2048
	ds_read_b128 v[116:119], v116 offset:3072
	s_add_u32 s28, s28, 0x40000
	s_addc_u32 s29, s29, 0
	s_mov_b32 m0, s31
	ds_read_b128 v[144:147], v183 offset:32768
	ds_read_b128 v[174:177], v183 offset:33792
	ds_read_b128 v[178:181], v183 offset:34816
	ds_read_b128 v[186:189], v183 offset:35840
	ds_read_b128 v[190:193], v183 offset:36864
	ds_read_b128 v[194:197], v183 offset:37888
	ds_read_b128 v[198:201], v183 offset:38912
	ds_read_b128 v[202:205], v183 offset:39936
	global_load_lds_dwordx4 v148, s[28:29]
	s_mov_b32 m0, s33
	s_nop 0
	global_load_lds_dwordx4 v162, s[28:29]
	s_waitcnt lgkmcnt(8)
	s_barrier
	s_waitcnt lgkmcnt(0)
	s_setprio 1
	s_waitcnt lgkmcnt(0)
	v_mfma_f32_16x16x32_bf16 v[140:143], v[96:99], v[144:147], v[140:143]
	v_mfma_f32_16x16x32_bf16 v[136:139], v[112:115], v[144:147], v[136:139]
	v_mfma_f32_16x16x32_bf16 v[124:127], v[96:99], v[178:181], v[124:127]
	v_mfma_f32_16x16x32_bf16 v[120:123], v[112:115], v[178:181], v[120:123]
	v_mfma_f32_16x16x32_bf16 v[92:95], v[96:99], v[190:193], v[92:95]
	v_mfma_f32_16x16x32_bf16 v[88:91], v[112:115], v[190:193], v[88:91]
	v_mfma_f32_16x16x32_bf16 v[76:79], v[96:99], v[198:201], v[76:79]
	v_mfma_f32_16x16x32_bf16 v[72:75], v[112:115], v[198:201], v[72:75]
	v_mfma_f32_16x16x32_bf16 v[140:143], v[100:103], v[174:177], v[140:143]
	v_mfma_f32_16x16x32_bf16 v[136:139], v[116:119], v[174:177], v[136:139]
	v_mfma_f32_16x16x32_bf16 v[124:127], v[100:103], v[186:189], v[124:127]
	v_mfma_f32_16x16x32_bf16 v[120:123], v[116:119], v[186:189], v[120:123]
	v_mfma_f32_16x16x32_bf16 v[92:95], v[100:103], v[194:197], v[92:95]
	v_mfma_f32_16x16x32_bf16 v[88:91], v[116:119], v[194:197], v[88:91]
	v_mfma_f32_16x16x32_bf16 v[76:79], v[100:103], v[202:205], v[76:79]
	v_mfma_f32_16x16x32_bf16 v[72:75], v[116:119], v[202:205], v[72:75]
	s_setprio 0
	s_barrier
	s_add_i32 s28, 0, 0x1c000
	s_add_i32 s29, s55, s5
	v_add_u32_e32 v185, s28, v159
	s_mov_b32 m0, s29
	ds_read_b128 v[206:209], v185
	ds_read_b128 v[210:213], v185 offset:1024
	ds_read_b128 v[214:217], v185 offset:2048
	ds_read_b128 v[218:221], v185 offset:3072
	global_load_lds_dwordx4 v150, s[98:99]
	s_add_i32 m0, s29, 0x2000
	s_nop 0
	global_load_lds_dwordx4 v164, s[98:99]
	s_barrier
; #define PG8_STAGE(bufoff, gbase, voff) do { _Pragma("unroll") for (int _i = 0; _i < 2; ++_i) \
;         __builtin_amdgcn_global_load_lds((const unsigned*)((const char*)(gbase) + (voff)[_i]), (LAS unsigned*)(lds + (bufoff) + ldsw + _i * 8192), 16, 0, 0); } while (0)
; #define PG8_LDA(dst, b, h) do { _Pragma("unroll") for (int m = 0; m < 4; ++m) _Pragma("unroll") for (int k = 0; k < 2; ++k) dst[m][k] = *(const LAS bf16x8*)(lds + PG8_SA(b, h) + aoff + m * 2048 + k * 1024); } while (0)
; #define PG8_MMA(ai, bj, At, Bt) do { __builtin_amdgcn_s_setprio(1); _Pragma("unroll") for (int m = 0; m < 4; ++m) _Pragma("unroll") for (int n = 0; n < 2; ++n) _Pragma("unroll") for (int k = 0; k < 2; ++k) \
;         acc[ai][bj][m][n] = __builtin_amdgcn_mfma_f32_16x16x32_bf16(Bt[n][k], At[m][k], acc[ai][bj][m][n], 0, 0, 0); __builtin_amdgcn_s_setprio(0); } while (0)
; #define PG8_WAIT_V(n) asm volatile("s_waitcnt vmcnt(" #n ")" ::: "memory")
; #define PG8_WAIT_L(n) asm volatile("s_waitcnt lgkmcnt(" #n ")" ::: "memory")
; #define PG8_BAR __builtin_amdgcn_s_barrier()
; #define PG8_SCHED __builtin_amdgcn_sched_barrier(0)
; template <class Epi, class Sched, bool ATILE = false>
; __device__ __forceinline__ void gemm_phase(LAS unsigned char* lds, const Gemm g, const Sched& S, const Epi& E) {
;     ...
;             PG8_BAR; PG8_WAIT_L(0); PG8_MMA(0, 1, At, B1); PG8_BAR;
;             PG8_LDA(At, 1, 1); PG8_STAGE(PG8_SA(1, 0), a3, voffA);
;             PG8_BAR; PG8_WAIT_L(0); PG8_MMA(1, 0, At, B0); PG8_BAR; PG8_SCHED;
;             PG8_STAGE(PG8_SB(1, 1), b3 + hstepB, voffB);
;             PG8_WAIT_V(6); PG8_BAR; PG8_MMA(1, 1, At, B1); PG8_BAR;
;         }
;         E(acc, cur, wr, wc, fr, fq);
;         if (!has_next) break;
	s_waitcnt lgkmcnt(0)
	s_setprio 1
	s_waitcnt lgkmcnt(0)
	v_mfma_f32_16x16x32_bf16 v[132:135], v[206:209], v[144:147], v[132:135]
	v_mfma_f32_16x16x32_bf16 v[128:131], v[214:217], v[144:147], v[128:131]
	v_mfma_f32_16x16x32_bf16 v[108:111], v[206:209], v[178:181], v[108:111]
	v_mfma_f32_16x16x32_bf16 v[104:107], v[214:217], v[178:181], v[104:107]
	v_mfma_f32_16x16x32_bf16 v[84:87], v[206:209], v[190:193], v[84:87]
	v_mfma_f32_16x16x32_bf16 v[80:83], v[214:217], v[190:193], v[80:83]
	v_mfma_f32_16x16x32_bf16 v[68:71], v[206:209], v[198:201], v[68:71]
	v_mfma_f32_16x16x32_bf16 v[64:67], v[214:217], v[198:201], v[64:67]
	v_mfma_f32_16x16x32_bf16 v[132:135], v[210:213], v[174:177], v[132:135]
	v_mfma_f32_16x16x32_bf16 v[128:131], v[218:221], v[174:177], v[128:131]
	v_mfma_f32_16x16x32_bf16 v[108:111], v[210:213], v[186:189], v[108:111]
	v_mfma_f32_16x16x32_bf16 v[104:107], v[218:221], v[186:189], v[104:107]
	v_mfma_f32_16x16x32_bf16 v[84:87], v[210:213], v[194:197], v[84:87]
	v_mfma_f32_16x16x32_bf16 v[80:83], v[218:221], v[194:197], v[80:83]
	v_mfma_f32_16x16x32_bf16 v[68:71], v[210:213], v[202:205], v[68:71]
	v_mfma_f32_16x16x32_bf16 v[64:67], v[218:221], v[202:205], v[64:67]
	s_setprio 0
	s_barrier
	s_mov_b32 m0, s35
	ds_read_b128 v[144:147], v183 offset:49152
	ds_read_b128 v[174:177], v183 offset:50176
	ds_read_b128 v[178:181], v183 offset:51200
	ds_read_b128 v[186:189], v183 offset:52224
	ds_read_b128 v[190:193], v183 offset:53248
	ds_read_b128 v[194:197], v183 offset:54272
	ds_read_b128 v[198:201], v183 offset:55296
	ds_read_b128 v[202:205], v183 offset:56320
	global_load_lds_dwordx4 v148, s[100:101]
	s_mov_b32 m0, s36
	s_nop 0
	global_load_lds_dwordx4 v162, s[100:101]
	s_barrier
	s_waitcnt lgkmcnt(0)
	s_setprio 1
	s_waitcnt lgkmcnt(0)
	v_mfma_f32_16x16x32_bf16 v[60:63], v[96:99], v[144:147], v[60:63]
	v_mfma_f32_16x16x32_bf16 v[56:59], v[112:115], v[144:147], v[56:59]
	v_mfma_f32_16x16x32_bf16 v[44:47], v[96:99], v[178:181], v[44:47]
	v_mfma_f32_16x16x32_bf16 v[40:43], v[112:115], v[178:181], v[40:43]
	v_mfma_f32_16x16x32_bf16 v[28:31], v[96:99], v[190:193], v[28:31]
	v_mfma_f32_16x16x32_bf16 v[24:27], v[112:115], v[190:193], v[24:27]
	v_mfma_f32_16x16x32_bf16 v[12:15], v[96:99], v[198:201], v[12:15]
	v_mfma_f32_16x16x32_bf16 v[8:11], v[112:115], v[198:201], v[8:11]
	v_mfma_f32_16x16x32_bf16 v[60:63], v[100:103], v[174:177], v[60:63]
	v_mfma_f32_16x16x32_bf16 v[56:59], v[116:119], v[174:177], v[56:59]
	v_mfma_f32_16x16x32_bf16 v[44:47], v[100:103], v[186:189], v[44:47]
	v_mfma_f32_16x16x32_bf16 v[40:43], v[116:119], v[186:189], v[40:43]
	v_mfma_f32_16x16x32_bf16 v[28:31], v[100:103], v[194:197], v[28:31]
	v_mfma_f32_16x16x32_bf16 v[24:27], v[116:119], v[194:197], v[24:27]
	v_mfma_f32_16x16x32_bf16 v[12:15], v[100:103], v[202:205], v[12:15]
	v_mfma_f32_16x16x32_bf16 v[8:11], v[116:119], v[202:205], v[8:11]
	s_setprio 0
	s_barrier
	s_add_u32 s26, s26, 0x40080
	s_addc_u32 s27, s27, 0
	s_add_i32 s28, s28, s5
	s_mov_b32 m0, s28
	s_nop 0
	global_load_lds_dwordx4 v150, s[26:27]
	s_add_i32 m0, s28, 0x2000
	s_nop 0
	global_load_lds_dwordx4 v164, s[26:27]
	s_waitcnt vmcnt(6)
	s_barrier
	s_setprio 1
	v_mfma_f32_16x16x32_bf16 v[52:55], v[206:209], v[144:147], v[52:55]
	v_mfma_f32_16x16x32_bf16 v[48:51], v[214:217], v[144:147], v[48:51]
	v_mfma_f32_16x16x32_bf16 v[36:39], v[206:209], v[178:181], v[36:39]
	v_mfma_f32_16x16x32_bf16 v[32:35], v[214:217], v[178:181], v[32:35]
	v_mfma_f32_16x16x32_bf16 v[20:23], v[206:209], v[190:193], v[20:23]
	v_mfma_f32_16x16x32_bf16 v[16:19], v[214:217], v[190:193], v[16:19]
	v_mfma_f32_16x16x32_bf16 v[4:7], v[206:209], v[198:201], v[4:7]
	v_mfma_f32_16x16x32_bf16 v[0:3], v[214:217], v[198:201], v[0:3]
	v_mfma_f32_16x16x32_bf16 v[52:55], v[210:213], v[174:177], v[52:55]
	v_mfma_f32_16x16x32_bf16 v[48:51], v[218:221], v[174:177], v[48:51]
	v_mfma_f32_16x16x32_bf16 v[36:39], v[210:213], v[186:189], v[36:39]
	v_mfma_f32_16x16x32_bf16 v[32:35], v[218:221], v[186:189], v[32:35]
	v_mfma_f32_16x16x32_bf16 v[20:23], v[210:213], v[194:197], v[20:23]
	v_mfma_f32_16x16x32_bf16 v[16:19], v[218:221], v[194:197], v[16:19]
	v_mfma_f32_16x16x32_bf16 v[4:7], v[210:213], v[202:205], v[4:7]
	v_mfma_f32_16x16x32_bf16 v[0:3], v[218:221], v[202:205], v[0:3]
	s_setprio 0
	s_barrier
	s_add_u32 s24, s24, 0x100
	s_addc_u32 s25, s25, 0
	s_add_u32 s52, s52, 0x100
	s_addc_u32 s53, s53, 0
	s_cmp_ge_i32 s54, s13
	s_mov_b32 s26, s54
	s_cbranch_scc0 .LBB0_1517
	s_branch .LBB0_1508

; #define PG8_STAGE(bufoff, gbase, voff) do { _Pragma("unroll") for (int _i = 0; _i < 2; ++_i) \
;         __builtin_amdgcn_global_load_lds((const unsigned*)((const char*)(gbase) + (voff)[_i]), (LAS unsigned*)(lds + (bufoff) + ldsw + _i * 8192), 16, 0, 0); } while (0)
; #define PG8_LDA(dst, b, h) do { _Pragma("unroll") for (int m = 0; m < 4; ++m) _Pragma("unroll") for (int k = 0; k < 2; ++k) dst[m][k] = *(const LAS bf16x8*)(lds + PG8_SA(b, h) + aoff + m * 2048 + k * 1024); } while (0)
; #define PG8_LDB(dst, b, h) do { _Pragma("unroll") for (int n = 0; n < 2; ++n) _Pragma("unroll") for (int k = 0; k < 2; ++k) dst[n][k] = *(const LAS bf16x8*)(lds + PG8_SB(b, h) + boff + n * 2048 + k * 1024); } while (0)
; #define PG8_MMA(ai, bj, At, Bt) do { __builtin_amdgcn_s_setprio(1); _Pragma("unroll") for (int m = 0; m < 4; ++m) _Pragma("unroll") for (int n = 0; n < 2; ++n) _Pragma("unroll") for (int k = 0; k < 2; ++k) \
;         acc[ai][bj][m][n] = __builtin_amdgcn_mfma_f32_16x16x32_bf16(Bt[n][k], At[m][k], acc[ai][bj][m][n], 0, 0, 0); __builtin_amdgcn_s_setprio(0); } while (0)
; #define PG8_WAIT_V(n) asm volatile("s_waitcnt vmcnt(" #n ")" ::: "memory")
; #define PG8_WAIT_L(n) asm volatile("s_waitcnt lgkmcnt(" #n ")" ::: "memory")
; template <class Epi, class Sched, bool ATILE = false>
; __device__ __forceinline__ void gemm_phase(LAS unsigned char* lds, const Gemm g, const Sched& S, const Epi& E) {
;     ...
;         for (int t = 0; t < nt; t += 2) {
;             const bool last = (t == nt - 2);
;             const char* a1 = cA + (size_t)(t + 1) * kstepA;
;             const char* a2 = last ? nA : cA + (size_t)(t + 2) * kstepA; const char* b2 = last ? nB : cB + (size_t)(t + 2) * kstep;
;             const char* a3 = a2 + kstepA; const char* b3 = b2 + kstep;
;             PG8_LDB(B0, 0, 0); PG8_SCHED; PG8_LDA(At, 0, 0); PG8_STAGE(PG8_SA(1, 1), a1 + hstepA, voffA);
;             PG8_WAIT_L(8); PG8_BAR; PG8_WAIT_L(0); PG8_MMA(0, 0, At, B0); PG8_BAR; PG8_SCHED;
;             PG8_LDB(B1, 0, 1); PG8_STAGE(PG8_SB(0, 0), b2, voffB);
;             PG8_BAR; PG8_WAIT_L(0); PG8_MMA(0, 1, At, B1); PG8_BAR;
;             PG8_LDA(At, 0, 1); PG8_STAGE(PG8_SA(0, 0), a2, voffA);
;             PG8_BAR; PG8_WAIT_L(0); PG8_MMA(1, 0, At, B0); PG8_BAR; PG8_SCHED;
;             PG8_STAGE(PG8_SB(0, 1), b2 + hstepB, voffB);
;             PG8_WAIT_V(6); PG8_BAR; PG8_MMA(1, 1, At, B1); PG8_BAR;
.LBB0_1658:
	s_waitcnt lgkmcnt(0)
	ds_read_b128 v[128:131], v169
	ds_read_b128 v[132:135], v169 offset:1024
	ds_read_b128 v[136:139], v169 offset:2048
	ds_read_b128 v[140:143], v169 offset:3072
	s_add_i32 s29, s27, 2
	s_add_u32 s34, s30, 0x4000
	s_addc_u32 s35, s31, 0
	s_cmp_eq_u32 s11, s27
	s_cselect_b32 s38, s22, s34
	s_cselect_b32 s39, s23, s35
	s_cselect_b32 s34, s24, s13
	s_cselect_b32 s35, s25, s17
	s_add_u32 s36, s38, 0x8000
	s_addc_u32 s37, s39, 0
	s_add_i32 m0, s5, 0xc000
	ds_read_b128 v[144:147], v210
	ds_read_b128 v[148:151], v210 offset:1024
	ds_read_b128 v[192:195], v210 offset:2048
	ds_read_b128 v[196:199], v210 offset:3072
	ds_read_b128 v[200:203], v210 offset:4096
	ds_read_b128 v[204:207], v210 offset:5120
	ds_read_b128 v[214:217], v210 offset:6144
	ds_read_b128 v[218:221], v210 offset:7168
	global_load_lds_dwordx4 v186, s[30:31]
	s_add_i32 m0, s5, 0xe000
	s_nop 0
	global_load_lds_dwordx4 v188, s[30:31]
	s_waitcnt lgkmcnt(8)
	s_barrier
	s_waitcnt lgkmcnt(0)
	s_setprio 1
	s_waitcnt lgkmcnt(0)
	v_mfma_f32_16x16x32_bf16 v[120:123], v[128:131], v[144:147], v[120:123]
	v_mfma_f32_16x16x32_bf16 v[116:119], v[136:139], v[144:147], v[116:119]
	v_mfma_f32_16x16x32_bf16 v[108:111], v[128:131], v[192:195], v[108:111]
	v_mfma_f32_16x16x32_bf16 v[100:103], v[136:139], v[192:195], v[100:103]
	v_mfma_f32_16x16x32_bf16 v[92:95], v[128:131], v[200:203], v[92:95]
	v_mfma_f32_16x16x32_bf16 v[84:87], v[136:139], v[200:203], v[84:87]
	v_mfma_f32_16x16x32_bf16 v[76:79], v[128:131], v[214:217], v[76:79]
	v_mfma_f32_16x16x32_bf16 v[68:71], v[136:139], v[214:217], v[68:71]
	v_mfma_f32_16x16x32_bf16 v[120:123], v[132:135], v[148:151], v[120:123]
	v_mfma_f32_16x16x32_bf16 v[116:119], v[140:143], v[148:151], v[116:119]
	v_mfma_f32_16x16x32_bf16 v[108:111], v[132:135], v[196:199], v[108:111]
	v_mfma_f32_16x16x32_bf16 v[100:103], v[140:143], v[196:199], v[100:103]
	v_mfma_f32_16x16x32_bf16 v[92:95], v[132:135], v[204:207], v[92:95]
	v_mfma_f32_16x16x32_bf16 v[84:87], v[140:143], v[204:207], v[84:87]
	v_mfma_f32_16x16x32_bf16 v[76:79], v[132:135], v[218:221], v[76:79]
	v_mfma_f32_16x16x32_bf16 v[68:71], v[140:143], v[218:221], v[68:71]
	s_setprio 0
	s_barrier
	s_add_i32 s27, s52, s4
	s_add_u32 s98, s34, s8
	s_addc_u32 s99, s35, s9
	s_mov_b32 m0, s27
	ds_read_b128 v[222:225], v211
	ds_read_b128 v[226:229], v211 offset:1024
	ds_read_b128 v[230:233], v211 offset:2048
	ds_read_b128 v[234:237], v211 offset:3072
	global_load_lds_dwordx4 v162, s[34:35]
	s_add_i32 m0, s27, 0x2000
	s_nop 0
	global_load_lds_dwordx4 v166, s[34:35]
	s_barrier
	s_waitcnt lgkmcnt(0)
	s_setprio 1
	s_waitcnt lgkmcnt(0)
	v_mfma_f32_16x16x32_bf16 v[124:127], v[222:225], v[144:147], v[124:127]
	v_mfma_f32_16x16x32_bf16 v[112:115], v[230:233], v[144:147], v[112:115]
	v_mfma_f32_16x16x32_bf16 v[104:107], v[222:225], v[192:195], v[104:107]
	v_mfma_f32_16x16x32_bf16 v[96:99], v[230:233], v[192:195], v[96:99]
	v_mfma_f32_16x16x32_bf16 v[88:91], v[222:225], v[200:203], v[88:91]
	v_mfma_f32_16x16x32_bf16 v[80:83], v[230:233], v[200:203], v[80:83]
	v_mfma_f32_16x16x32_bf16 v[72:75], v[222:225], v[214:217], v[72:75]
	v_mfma_f32_16x16x32_bf16 v[64:67], v[230:233], v[214:217], v[64:67]
	v_mfma_f32_16x16x32_bf16 v[124:127], v[226:229], v[148:151], v[124:127]
	v_mfma_f32_16x16x32_bf16 v[112:115], v[234:237], v[148:151], v[112:115]
	v_mfma_f32_16x16x32_bf16 v[104:107], v[226:229], v[196:199], v[104:107]
	v_mfma_f32_16x16x32_bf16 v[96:99], v[234:237], v[196:199], v[96:99]
	v_mfma_f32_16x16x32_bf16 v[88:91], v[226:229], v[204:207], v[88:91]
	v_mfma_f32_16x16x32_bf16 v[80:83], v[234:237], v[204:207], v[80:83]
	v_mfma_f32_16x16x32_bf16 v[72:75], v[226:229], v[218:221], v[72:75]
	v_mfma_f32_16x16x32_bf16 v[64:67], v[234:237], v[218:221], v[64:67]
	s_setprio 0
	s_barrier
	s_mov_b32 m0, s5
	ds_read_b128 v[144:147], v210 offset:16384
	ds_read_b128 v[148:151], v210 offset:17408
	ds_read_b128 v[192:195], v210 offset:18432
	ds_read_b128 v[196:199], v210 offset:19456
	ds_read_b128 v[200:203], v210 offset:20480
	ds_read_b128 v[204:207], v210 offset:21504
	ds_read_b128 v[214:217], v210 offset:22528
	ds_read_b128 v[218:221], v210 offset:23552
	global_load_lds_dwordx4 v160, s[38:39]
	s_mov_b32 m0, s33
	s_nop 0
	global_load_lds_dwordx4 v164, s[38:39]
	s_barrier
	s_waitcnt lgkmcnt(0)
	s_setprio 1
	s_waitcnt lgkmcnt(0)
	v_mfma_f32_16x16x32_bf16 v[60:63], v[128:131], v[144:147], v[60:63]
	v_mfma_f32_16x16x32_bf16 v[56:59], v[136:139], v[144:147], v[56:59]
	v_mfma_f32_16x16x32_bf16 v[44:47], v[128:131], v[192:195], v[44:47]
	v_mfma_f32_16x16x32_bf16 v[40:43], v[136:139], v[192:195], v[40:43]
	v_mfma_f32_16x16x32_bf16 v[28:31], v[128:131], v[200:203], v[28:31]
	v_mfma_f32_16x16x32_bf16 v[24:27], v[136:139], v[200:203], v[24:27]
	v_mfma_f32_16x16x32_bf16 v[12:15], v[128:131], v[214:217], v[12:15]
	v_mfma_f32_16x16x32_bf16 v[8:11], v[136:139], v[214:217], v[8:11]
	v_mfma_f32_16x16x32_bf16 v[60:63], v[132:135], v[148:151], v[60:63]
	v_mfma_f32_16x16x32_bf16 v[56:59], v[140:143], v[148:151], v[56:59]
	v_mfma_f32_16x16x32_bf16 v[44:47], v[132:135], v[196:199], v[44:47]
	v_mfma_f32_16x16x32_bf16 v[40:43], v[140:143], v[196:199], v[40:43]
	v_mfma_f32_16x16x32_bf16 v[28:31], v[132:135], v[204:207], v[28:31]
	v_mfma_f32_16x16x32_bf16 v[24:27], v[140:143], v[204:207], v[24:27]
	v_mfma_f32_16x16x32_bf16 v[12:15], v[132:135], v[218:221], v[12:15]
	v_mfma_f32_16x16x32_bf16 v[8:11], v[140:143], v[218:221], v[8:11]
	s_setprio 0
	s_barrier
	s_add_u32 s56, s34, 0x80000
	s_addc_u32 s57, s35, 0
	s_add_i32 s27, s53, s4
	s_mov_b32 m0, s27
	s_nop 0
	global_load_lds_dwordx4 v162, s[56:57]
	s_add_i32 m0, s27, 0x2000
	s_nop 0
	global_load_lds_dwordx4 v166, s[56:57]
	s_waitcnt vmcnt(6)
	s_barrier
; #define PG8_STAGE(bufoff, gbase, voff) do { _Pragma("unroll") for (int _i = 0; _i < 2; ++_i) \
;         __builtin_amdgcn_global_load_lds((const unsigned*)((const char*)(gbase) + (voff)[_i]), (LAS unsigned*)(lds + (bufoff) + ldsw + _i * 8192), 16, 0, 0); } while (0)
; #define PG8_LDA(dst, b, h) do { _Pragma("unroll") for (int m = 0; m < 4; ++m) _Pragma("unroll") for (int k = 0; k < 2; ++k) dst[m][k] = *(const LAS bf16x8*)(lds + PG8_SA(b, h) + aoff + m * 2048 + k * 1024); } while (0)
; #define PG8_LDB(dst, b, h) do { _Pragma("unroll") for (int n = 0; n < 2; ++n) _Pragma("unroll") for (int k = 0; k < 2; ++k) dst[n][k] = *(const LAS bf16x8*)(lds + PG8_SB(b, h) + boff + n * 2048 + k * 1024); } while (0)
; #define PG8_MMA(ai, bj, At, Bt) do { __builtin_amdgcn_s_setprio(1); _Pragma("unroll") for (int m = 0; m < 4; ++m) _Pragma("unroll") for (int n = 0; n < 2; ++n) _Pragma("unroll") for (int k = 0; k < 2; ++k) \
;         acc[ai][bj][m][n] = __builtin_amdgcn_mfma_f32_16x16x32_bf16(Bt[n][k], At[m][k], acc[ai][bj][m][n], 0, 0, 0); __builtin_amdgcn_s_setprio(0); } while (0)
; #define PG8_WAIT_V(n) asm volatile("s_waitcnt vmcnt(" #n ")" ::: "memory")
; #define PG8_WAIT_L(n) asm volatile("s_waitcnt lgkmcnt(" #n ")" ::: "memory")
; #define PG8_BAR __builtin_amdgcn_s_barrier()
; #define PG8_SCHED __builtin_amdgcn_sched_barrier(0)
; template <class Epi, class Sched, bool ATILE = false>
; __device__ __forceinline__ void gemm_phase(LAS unsigned char* lds, const Gemm g, const Sched& S, const Epi& E) {
;     ...
;             PG8_WAIT_V(6); PG8_BAR; PG8_MMA(1, 1, At, B1); PG8_BAR;
;             PG8_LDB(B0, 1, 0); PG8_SCHED; PG8_LDA(At, 1, 0); PG8_STAGE(PG8_SA(0, 1), a2 + hstepA, voffA);
;             PG8_WAIT_L(8); PG8_BAR; PG8_WAIT_L(0); PG8_MMA(0, 0, At, B0); PG8_BAR; PG8_SCHED;
;             PG8_LDB(B1, 1, 1); PG8_STAGE(PG8_SB(1, 0), b3, voffB);
;             PG8_BAR; PG8_WAIT_L(0); PG8_MMA(0, 1, At, B1); PG8_BAR;
	s_setprio 1
	v_mfma_f32_16x16x32_bf16 v[52:55], v[222:225], v[144:147], v[52:55]
	v_mfma_f32_16x16x32_bf16 v[48:51], v[230:233], v[144:147], v[48:51]
	v_mfma_f32_16x16x32_bf16 v[36:39], v[222:225], v[192:195], v[36:39]
	v_mfma_f32_16x16x32_bf16 v[32:35], v[230:233], v[192:195], v[32:35]
	v_mfma_f32_16x16x32_bf16 v[20:23], v[222:225], v[200:203], v[20:23]
	v_mfma_f32_16x16x32_bf16 v[16:19], v[230:233], v[200:203], v[16:19]
	v_mfma_f32_16x16x32_bf16 v[4:7], v[222:225], v[214:217], v[4:7]
	v_mfma_f32_16x16x32_bf16 v[0:3], v[230:233], v[214:217], v[0:3]
	v_mfma_f32_16x16x32_bf16 v[52:55], v[226:229], v[148:151], v[52:55]
	v_mfma_f32_16x16x32_bf16 v[48:51], v[234:237], v[148:151], v[48:51]
	v_mfma_f32_16x16x32_bf16 v[36:39], v[226:229], v[196:199], v[36:39]
	v_mfma_f32_16x16x32_bf16 v[32:35], v[234:237], v[196:199], v[32:35]
	v_mfma_f32_16x16x32_bf16 v[20:23], v[226:229], v[204:207], v[20:23]
	v_mfma_f32_16x16x32_bf16 v[16:19], v[234:237], v[204:207], v[16:19]
	v_mfma_f32_16x16x32_bf16 v[4:7], v[226:229], v[218:221], v[4:7]
	v_mfma_f32_16x16x32_bf16 v[0:3], v[234:237], v[218:221], v[0:3]
	s_setprio 0
	s_barrier
	s_add_i32 s27, 0, 0x18000
	v_add_u32_e32 v140, s27, v157
	ds_read_b128 v[128:131], v140
	ds_read_b128 v[132:135], v140 offset:1024
	ds_read_b128 v[136:139], v140 offset:2048
	ds_read_b128 v[140:143], v140 offset:3072
	s_add_u32 s38, s38, 0x4000
	s_addc_u32 s39, s39, 0
	s_mov_b32 m0, s40
	ds_read_b128 v[144:147], v210 offset:32768
	ds_read_b128 v[148:151], v210 offset:33792
	ds_read_b128 v[192:195], v210 offset:34816
	ds_read_b128 v[196:199], v210 offset:35840
	ds_read_b128 v[200:203], v210 offset:36864
	ds_read_b128 v[204:207], v210 offset:37888
	ds_read_b128 v[214:217], v210 offset:38912
	ds_read_b128 v[218:221], v210 offset:39936
	global_load_lds_dwordx4 v160, s[38:39]
	s_mov_b32 m0, s41
	s_nop 0
	global_load_lds_dwordx4 v164, s[38:39]
	s_waitcnt lgkmcnt(8)
	s_barrier
	s_waitcnt lgkmcnt(0)
	s_setprio 1
	s_waitcnt lgkmcnt(0)
	v_mfma_f32_16x16x32_bf16 v[120:123], v[128:131], v[144:147], v[120:123]
	v_mfma_f32_16x16x32_bf16 v[116:119], v[136:139], v[144:147], v[116:119]
	v_mfma_f32_16x16x32_bf16 v[108:111], v[128:131], v[192:195], v[108:111]
	v_mfma_f32_16x16x32_bf16 v[100:103], v[136:139], v[192:195], v[100:103]
	v_mfma_f32_16x16x32_bf16 v[92:95], v[128:131], v[200:203], v[92:95]
	v_mfma_f32_16x16x32_bf16 v[84:87], v[136:139], v[200:203], v[84:87]
	v_mfma_f32_16x16x32_bf16 v[76:79], v[128:131], v[214:217], v[76:79]
	v_mfma_f32_16x16x32_bf16 v[68:71], v[136:139], v[214:217], v[68:71]
	v_mfma_f32_16x16x32_bf16 v[120:123], v[132:135], v[148:151], v[120:123]
	v_mfma_f32_16x16x32_bf16 v[116:119], v[140:143], v[148:151], v[116:119]
	v_mfma_f32_16x16x32_bf16 v[108:111], v[132:135], v[196:199], v[108:111]
	v_mfma_f32_16x16x32_bf16 v[100:103], v[140:143], v[196:199], v[100:103]
	v_mfma_f32_16x16x32_bf16 v[92:95], v[132:135], v[204:207], v[92:95]
	v_mfma_f32_16x16x32_bf16 v[84:87], v[140:143], v[204:207], v[84:87]
	v_mfma_f32_16x16x32_bf16 v[76:79], v[132:135], v[218:221], v[76:79]
	v_mfma_f32_16x16x32_bf16 v[68:71], v[140:143], v[218:221], v[68:71]
	s_setprio 0
	s_barrier
	s_add_i32 s38, 0, 0x1c000
	s_add_i32 s27, s27, s4
	v_add_u32_e32 v213, s38, v157
	s_mov_b32 m0, s27
	ds_read_b128 v[222:225], v213
	ds_read_b128 v[226:229], v213 offset:1024
	ds_read_b128 v[230:233], v213 offset:2048
	ds_read_b128 v[234:237], v213 offset:3072
	global_load_lds_dwordx4 v162, s[98:99]
	s_add_i32 m0, s27, 0x2000
	s_nop 0
	global_load_lds_dwordx4 v166, s[98:99]
	s_barrier
; #define PG8_STAGE(bufoff, gbase, voff) do { _Pragma("unroll") for (int _i = 0; _i < 2; ++_i) \
;         __builtin_amdgcn_global_load_lds((const unsigned*)((const char*)(gbase) + (voff)[_i]), (LAS unsigned*)(lds + (bufoff) + ldsw + _i * 8192), 16, 0, 0); } while (0)
; #define PG8_LDA(dst, b, h) do { _Pragma("unroll") for (int m = 0; m < 4; ++m) _Pragma("unroll") for (int k = 0; k < 2; ++k) dst[m][k] = *(const LAS bf16x8*)(lds + PG8_SA(b, h) + aoff + m * 2048 + k * 1024); } while (0)
; #define PG8_MMA(ai, bj, At, Bt) do { __builtin_amdgcn_s_setprio(1); _Pragma("unroll") for (int m = 0; m < 4; ++m) _Pragma("unroll") for (int n = 0; n < 2; ++n) _Pragma("unroll") for (int k = 0; k < 2; ++k) \
;         acc[ai][bj][m][n] = __builtin_amdgcn_mfma_f32_16x16x32_bf16(Bt[n][k], At[m][k], acc[ai][bj][m][n], 0, 0, 0); __builtin_amdgcn_s_setprio(0); } while (0)
; #define PG8_WAIT_V(n) asm volatile("s_waitcnt vmcnt(" #n ")" ::: "memory")
; #define PG8_WAIT_L(n) asm volatile("s_waitcnt lgkmcnt(" #n ")" ::: "memory")
; #define PG8_BAR __builtin_amdgcn_s_barrier()
; #define PG8_SCHED __builtin_amdgcn_sched_barrier(0)
; template <class Epi, class Sched, bool ATILE = false>
; __device__ __forceinline__ void gemm_phase(LAS unsigned char* lds, const Gemm g, const Sched& S, const Epi& E) {
;     ...
;             PG8_BAR; PG8_WAIT_L(0); PG8_MMA(0, 1, At, B1); PG8_BAR;
;             PG8_LDA(At, 1, 1); PG8_STAGE(PG8_SA(1, 0), a3, voffA);
;             PG8_BAR; PG8_WAIT_L(0); PG8_MMA(1, 0, At, B0); PG8_BAR; PG8_SCHED;
;             PG8_STAGE(PG8_SB(1, 1), b3 + hstepB, voffB);
;             PG8_WAIT_V(6); PG8_BAR; PG8_MMA(1, 1, At, B1); PG8_BAR;
;         }
;         E(acc, cur, wr, wc, fr, fq);
;         if (!has_next) break;
	s_waitcnt lgkmcnt(0)
	s_setprio 1
	s_waitcnt lgkmcnt(0)
	v_mfma_f32_16x16x32_bf16 v[124:127], v[222:225], v[144:147], v[124:127]
	v_mfma_f32_16x16x32_bf16 v[112:115], v[230:233], v[144:147], v[112:115]
	v_mfma_f32_16x16x32_bf16 v[104:107], v[222:225], v[192:195], v[104:107]
	v_mfma_f32_16x16x32_bf16 v[96:99], v[230:233], v[192:195], v[96:99]
	v_mfma_f32_16x16x32_bf16 v[88:91], v[222:225], v[200:203], v[88:91]
	v_mfma_f32_16x16x32_bf16 v[80:83], v[230:233], v[200:203], v[80:83]
	v_mfma_f32_16x16x32_bf16 v[72:75], v[222:225], v[214:217], v[72:75]
	v_mfma_f32_16x16x32_bf16 v[64:67], v[230:233], v[214:217], v[64:67]
	v_mfma_f32_16x16x32_bf16 v[124:127], v[226:229], v[148:151], v[124:127]
	v_mfma_f32_16x16x32_bf16 v[112:115], v[234:237], v[148:151], v[112:115]
	v_mfma_f32_16x16x32_bf16 v[104:107], v[226:229], v[196:199], v[104:107]
	v_mfma_f32_16x16x32_bf16 v[96:99], v[234:237], v[196:199], v[96:99]
	v_mfma_f32_16x16x32_bf16 v[88:91], v[226:229], v[204:207], v[88:91]
	v_mfma_f32_16x16x32_bf16 v[80:83], v[234:237], v[204:207], v[80:83]
	v_mfma_f32_16x16x32_bf16 v[72:75], v[226:229], v[218:221], v[72:75]
	v_mfma_f32_16x16x32_bf16 v[64:67], v[234:237], v[218:221], v[64:67]
	s_setprio 0
	s_barrier
	s_mov_b32 m0, s43
	ds_read_b128 v[144:147], v210 offset:49152
	ds_read_b128 v[148:151], v210 offset:50176
	ds_read_b128 v[192:195], v210 offset:51200
	ds_read_b128 v[196:199], v210 offset:52224
	ds_read_b128 v[200:203], v210 offset:53248
	ds_read_b128 v[204:207], v210 offset:54272
	ds_read_b128 v[214:217], v210 offset:55296
	ds_read_b128 v[218:221], v210 offset:56320
	global_load_lds_dwordx4 v160, s[36:37]
	s_mov_b32 m0, s44
	s_nop 0
	global_load_lds_dwordx4 v164, s[36:37]
	s_barrier
	s_waitcnt lgkmcnt(0)
	s_setprio 1
	s_waitcnt lgkmcnt(0)
	v_mfma_f32_16x16x32_bf16 v[60:63], v[128:131], v[144:147], v[60:63]
	v_mfma_f32_16x16x32_bf16 v[56:59], v[136:139], v[144:147], v[56:59]
	v_mfma_f32_16x16x32_bf16 v[44:47], v[128:131], v[192:195], v[44:47]
	v_mfma_f32_16x16x32_bf16 v[40:43], v[136:139], v[192:195], v[40:43]
	v_mfma_f32_16x16x32_bf16 v[28:31], v[128:131], v[200:203], v[28:31]
	v_mfma_f32_16x16x32_bf16 v[24:27], v[136:139], v[200:203], v[24:27]
	v_mfma_f32_16x16x32_bf16 v[12:15], v[128:131], v[214:217], v[12:15]
	v_mfma_f32_16x16x32_bf16 v[8:11], v[136:139], v[214:217], v[8:11]
	v_mfma_f32_16x16x32_bf16 v[60:63], v[132:135], v[148:151], v[60:63]
	v_mfma_f32_16x16x32_bf16 v[56:59], v[140:143], v[148:151], v[56:59]
	v_mfma_f32_16x16x32_bf16 v[44:47], v[132:135], v[196:199], v[44:47]
	v_mfma_f32_16x16x32_bf16 v[40:43], v[140:143], v[196:199], v[40:43]
	v_mfma_f32_16x16x32_bf16 v[28:31], v[132:135], v[204:207], v[28:31]
	v_mfma_f32_16x16x32_bf16 v[24:27], v[140:143], v[204:207], v[24:27]
	v_mfma_f32_16x16x32_bf16 v[12:15], v[132:135], v[218:221], v[12:15]
	v_mfma_f32_16x16x32_bf16 v[8:11], v[140:143], v[218:221], v[8:11]
	s_setprio 0
	s_barrier
	s_add_u32 s34, s34, 0x80080
	s_addc_u32 s35, s35, 0
	s_add_i32 s27, s38, s4
	s_mov_b32 m0, s27
	s_nop 0
	global_load_lds_dwordx4 v162, s[34:35]
	s_add_i32 m0, s27, 0x2000
	s_nop 0
	global_load_lds_dwordx4 v166, s[34:35]
	s_waitcnt vmcnt(6)
	s_barrier
	s_setprio 1
	v_mfma_f32_16x16x32_bf16 v[52:55], v[222:225], v[144:147], v[52:55]
	v_mfma_f32_16x16x32_bf16 v[48:51], v[230:233], v[144:147], v[48:51]
	v_mfma_f32_16x16x32_bf16 v[36:39], v[222:225], v[192:195], v[36:39]
	v_mfma_f32_16x16x32_bf16 v[32:35], v[230:233], v[192:195], v[32:35]
	v_mfma_f32_16x16x32_bf16 v[20:23], v[222:225], v[200:203], v[20:23]
	v_mfma_f32_16x16x32_bf16 v[16:19], v[230:233], v[200:203], v[16:19]
	v_mfma_f32_16x16x32_bf16 v[4:7], v[222:225], v[214:217], v[4:7]
	v_mfma_f32_16x16x32_bf16 v[0:3], v[230:233], v[214:217], v[0:3]
	v_mfma_f32_16x16x32_bf16 v[52:55], v[226:229], v[148:151], v[52:55]
	v_mfma_f32_16x16x32_bf16 v[48:51], v[234:237], v[148:151], v[48:51]
	v_mfma_f32_16x16x32_bf16 v[36:39], v[226:229], v[196:199], v[36:39]
	v_mfma_f32_16x16x32_bf16 v[32:35], v[234:237], v[196:199], v[32:35]
	v_mfma_f32_16x16x32_bf16 v[20:23], v[226:229], v[204:207], v[20:23]
	v_mfma_f32_16x16x32_bf16 v[16:19], v[234:237], v[204:207], v[16:19]
	v_mfma_f32_16x16x32_bf16 v[4:7], v[226:229], v[218:221], v[4:7]
	v_mfma_f32_16x16x32_bf16 v[0:3], v[234:237], v[218:221], v[0:3]
	s_setprio 0
	s_barrier
	s_add_u32 s13, s13, 0x100
	s_addc_u32 s17, s17, 0
	s_add_u32 s30, s30, 0x10000
	s_addc_u32 s31, s31, 0
	s_cmp_ge_i32 s29, s1
	s_mov_b32 s27, s29
	s_cbranch_scc0 .LBB0_1658
	s_branch .LBB0_1662

; #define PG8_STAGE(bufoff, gbase, voff) do { _Pragma("unroll") for (int _i = 0; _i < 2; ++_i) \
;         __builtin_amdgcn_global_load_lds((const unsigned*)((const char*)(gbase) + (voff)[_i]), (LAS unsigned*)(lds + (bufoff) + ldsw + _i * 8192), 16, 0, 0); } while (0)
; #define PG8_LDA(dst, b, h) do { _Pragma("unroll") for (int m = 0; m < 4; ++m) _Pragma("unroll") for (int k = 0; k < 2; ++k) dst[m][k] = *(const LAS bf16x8*)(lds + PG8_SA(b, h) + aoff + m * 2048 + k * 1024); } while (0)
; #define PG8_LDB(dst, b, h) do { _Pragma("unroll") for (int n = 0; n < 2; ++n) _Pragma("unroll") for (int k = 0; k < 2; ++k) dst[n][k] = *(const LAS bf16x8*)(lds + PG8_SB(b, h) + boff + n * 2048 + k * 1024); } while (0)
; #define PG8_MMA(ai, bj, At, Bt) do { __builtin_amdgcn_s_setprio(1); _Pragma("unroll") for (int m = 0; m < 4; ++m) _Pragma("unroll") for (int n = 0; n < 2; ++n) _Pragma("unroll") for (int k = 0; k < 2; ++k) \
;         acc[ai][bj][m][n] = __builtin_amdgcn_mfma_f32_16x16x32_bf16(Bt[n][k], At[m][k], acc[ai][bj][m][n], 0, 0, 0); __builtin_amdgcn_s_setprio(0); } while (0)
; #define PG8_WAIT_V(n) asm volatile("s_waitcnt vmcnt(" #n ")" ::: "memory")
; #define PG8_WAIT_L(n) asm volatile("s_waitcnt lgkmcnt(" #n ")" ::: "memory")
; template <class Epi, class Sched, bool ATILE = false>
; __device__ __forceinline__ void gemm_phase(LAS unsigned char* lds, const Gemm g, const Sched& S, const Epi& E) {
;     ...
;         for (int t = 0; t < nt; t += 2) {
;             const bool last = (t == nt - 2);
;             const char* a1 = cA + (size_t)(t + 1) * kstepA;
;             const char* a2 = last ? nA : cA + (size_t)(t + 2) * kstepA; const char* b2 = last ? nB : cB + (size_t)(t + 2) * kstep;
;             const char* a3 = a2 + kstepA; const char* b3 = b2 + kstep;
;             PG8_LDB(B0, 0, 0); PG8_SCHED; PG8_LDA(At, 0, 0); PG8_STAGE(PG8_SA(1, 1), a1 + hstepA, voffA);
;             PG8_WAIT_L(8); PG8_BAR; PG8_WAIT_L(0); PG8_MMA(0, 0, At, B0); PG8_BAR; PG8_SCHED;
;             PG8_LDB(B1, 0, 1); PG8_STAGE(PG8_SB(0, 0), b2, voffB);
;             PG8_BAR; PG8_WAIT_L(0); PG8_MMA(0, 1, At, B1); PG8_BAR;
;             PG8_LDA(At, 0, 1); PG8_STAGE(PG8_SA(0, 0), a2, voffA);
;             PG8_BAR; PG8_WAIT_L(0); PG8_MMA(1, 0, At, B0); PG8_BAR; PG8_SCHED;
;             PG8_STAGE(PG8_SB(0, 1), b2 + hstepB, voffB);
;             PG8_WAIT_V(6); PG8_BAR; PG8_MMA(1, 1, At, B1); PG8_BAR;
.LBB0_1812:
	ds_read_b128 v[176:179], v139
	ds_read_b128 v[180:183], v139 offset:1024
	ds_read_b128 v[184:187], v139 offset:2048
	ds_read_b128 v[188:191], v139 offset:3072
	s_add_i32 s34, s8, 2
	s_add_u32 s9, s6, 0xfff80080
	s_addc_u32 s10, s7, -1
	s_cmp_eq_u32 s19, s8
	s_cselect_b32 s8, s18, s25
	s_cselect_b32 s11, s13, s10
	s_cselect_b32 s10, s16, s9
	s_cselect_b32 s9, s17, s27
	s_add_i32 m0, s37, 0xc000
	ds_read_b128 v[192:195], v159
	ds_read_b128 v[196:199], v159 offset:1024
	ds_read_b128 v[200:203], v159 offset:2048
	ds_read_b128 v[204:207], v159 offset:3072
	ds_read_b128 v[208:211], v159 offset:4096
	ds_read_b128 v[212:215], v159 offset:5120
	ds_read_b128 v[216:219], v159 offset:6144
	ds_read_b128 v[220:223], v159 offset:7168
	global_load_lds_dwordx4 v164, s[6:7]
	s_add_i32 m0, s37, 0xe000
	s_nop 0
	global_load_lds_dwordx4 v166, s[6:7]
	s_waitcnt lgkmcnt(8)
	s_barrier
	s_waitcnt lgkmcnt(0)
	s_setprio 1
	s_waitcnt lgkmcnt(0)
	v_mfma_f32_16x16x32_bf16 v[120:123], v[176:179], v[192:195], v[120:123]
	v_mfma_f32_16x16x32_bf16 v[112:115], v[184:187], v[192:195], v[112:115]
	v_mfma_f32_16x16x32_bf16 v[104:107], v[176:179], v[200:203], v[104:107]
	v_mfma_f32_16x16x32_bf16 v[96:99], v[184:187], v[200:203], v[96:99]
	v_mfma_f32_16x16x32_bf16 v[88:91], v[176:179], v[208:211], v[88:91]
	v_mfma_f32_16x16x32_bf16 v[80:83], v[184:187], v[208:211], v[80:83]
	v_mfma_f32_16x16x32_bf16 v[72:75], v[176:179], v[216:219], v[72:75]
	v_mfma_f32_16x16x32_bf16 v[64:67], v[184:187], v[216:219], v[64:67]
	v_mfma_f32_16x16x32_bf16 v[120:123], v[180:183], v[196:199], v[120:123]
	v_mfma_f32_16x16x32_bf16 v[112:115], v[188:191], v[196:199], v[112:115]
	v_mfma_f32_16x16x32_bf16 v[104:107], v[180:183], v[204:207], v[104:107]
	v_mfma_f32_16x16x32_bf16 v[96:99], v[188:191], v[204:207], v[96:99]
	v_mfma_f32_16x16x32_bf16 v[88:91], v[180:183], v[212:215], v[88:91]
	v_mfma_f32_16x16x32_bf16 v[80:83], v[188:191], v[212:215], v[80:83]
	v_mfma_f32_16x16x32_bf16 v[72:75], v[180:183], v[220:223], v[72:75]
	v_mfma_f32_16x16x32_bf16 v[64:67], v[188:191], v[220:223], v[64:67]
	s_setprio 0
	s_barrier
	s_add_i32 s35, s51, s36
	s_add_u32 s98, s8, s22
	s_addc_u32 s99, s9, s23
	s_mov_b32 m0, s35
	ds_read_b128 v[224:227], v173
	ds_read_b128 v[228:231], v173 offset:1024
	ds_read_b128 v[232:235], v173 offset:2048
	ds_read_b128 v[236:239], v173 offset:3072
	global_load_lds_dwordx4 v130, s[8:9]
	s_add_i32 m0, s35, 0x2000
	s_nop 0
	global_load_lds_dwordx4 v134, s[8:9]
	s_barrier
	s_waitcnt lgkmcnt(0)
	s_setprio 1
	s_waitcnt lgkmcnt(0)
	v_mfma_f32_16x16x32_bf16 v[124:127], v[224:227], v[192:195], v[124:127]
	v_mfma_f32_16x16x32_bf16 v[116:119], v[232:235], v[192:195], v[116:119]
	v_mfma_f32_16x16x32_bf16 v[108:111], v[224:227], v[200:203], v[108:111]
	v_mfma_f32_16x16x32_bf16 v[100:103], v[232:235], v[200:203], v[100:103]
	v_mfma_f32_16x16x32_bf16 v[92:95], v[224:227], v[208:211], v[92:95]
	v_mfma_f32_16x16x32_bf16 v[84:87], v[232:235], v[208:211], v[84:87]
	v_mfma_f32_16x16x32_bf16 v[76:79], v[224:227], v[216:219], v[76:79]
	v_mfma_f32_16x16x32_bf16 v[68:71], v[232:235], v[216:219], v[68:71]
	v_mfma_f32_16x16x32_bf16 v[124:127], v[228:231], v[196:199], v[124:127]
	v_mfma_f32_16x16x32_bf16 v[116:119], v[236:239], v[196:199], v[116:119]
	v_mfma_f32_16x16x32_bf16 v[108:111], v[228:231], v[204:207], v[108:111]
	v_mfma_f32_16x16x32_bf16 v[100:103], v[236:239], v[204:207], v[100:103]
	v_mfma_f32_16x16x32_bf16 v[92:95], v[228:231], v[212:215], v[92:95]
	v_mfma_f32_16x16x32_bf16 v[84:87], v[236:239], v[212:215], v[84:87]
	v_mfma_f32_16x16x32_bf16 v[76:79], v[228:231], v[220:223], v[76:79]
	v_mfma_f32_16x16x32_bf16 v[68:71], v[236:239], v[220:223], v[68:71]
	s_setprio 0
	s_barrier
	s_mov_b32 m0, s37
	s_add_u32 s100, s10, s22
	s_addc_u32 s101, s11, s23
	ds_read_b128 v[192:195], v159 offset:16384
	ds_read_b128 v[196:199], v159 offset:17408
	ds_read_b128 v[200:203], v159 offset:18432
	ds_read_b128 v[204:207], v159 offset:19456
	ds_read_b128 v[208:211], v159 offset:20480
	ds_read_b128 v[212:215], v159 offset:21504
	ds_read_b128 v[216:219], v159 offset:22528
	ds_read_b128 v[220:223], v159 offset:23552
	global_load_lds_dwordx4 v128, s[10:11]
	s_mov_b32 m0, s38
	s_nop 0
	global_load_lds_dwordx4 v132, s[10:11]
	s_barrier
	s_waitcnt lgkmcnt(0)
	s_setprio 1
	s_waitcnt lgkmcnt(0)
	v_mfma_f32_16x16x32_bf16 v[56:59], v[176:179], v[192:195], v[56:59]
	v_mfma_f32_16x16x32_bf16 v[48:51], v[184:187], v[192:195], v[48:51]
	v_mfma_f32_16x16x32_bf16 v[40:43], v[176:179], v[200:203], v[40:43]
	v_mfma_f32_16x16x32_bf16 v[32:35], v[184:187], v[200:203], v[32:35]
	v_mfma_f32_16x16x32_bf16 v[24:27], v[176:179], v[208:211], v[24:27]
	v_mfma_f32_16x16x32_bf16 v[16:19], v[184:187], v[208:211], v[16:19]
	v_mfma_f32_16x16x32_bf16 v[8:11], v[176:179], v[216:219], v[8:11]
	v_mfma_f32_16x16x32_bf16 v[4:7], v[184:187], v[216:219], v[4:7]
	v_mfma_f32_16x16x32_bf16 v[56:59], v[180:183], v[196:199], v[56:59]
	v_mfma_f32_16x16x32_bf16 v[48:51], v[188:191], v[196:199], v[48:51]
	v_mfma_f32_16x16x32_bf16 v[40:43], v[180:183], v[204:207], v[40:43]
	v_mfma_f32_16x16x32_bf16 v[32:35], v[188:191], v[204:207], v[32:35]
	v_mfma_f32_16x16x32_bf16 v[24:27], v[180:183], v[212:215], v[24:27]
	v_mfma_f32_16x16x32_bf16 v[16:19], v[188:191], v[212:215], v[16:19]
	v_mfma_f32_16x16x32_bf16 v[8:11], v[180:183], v[220:223], v[8:11]
	v_mfma_f32_16x16x32_bf16 v[4:7], v[188:191], v[220:223], v[4:7]
	s_setprio 0
	s_barrier
	s_add_u32 s54, s8, 0x80000
	s_addc_u32 s55, s9, 0
	s_add_i32 s35, s52, s36
	s_mov_b32 m0, s35
	s_nop 0
	global_load_lds_dwordx4 v130, s[54:55]
	s_add_i32 m0, s35, 0x2000
	s_nop 0
	global_load_lds_dwordx4 v134, s[54:55]
	s_waitcnt vmcnt(6)
	s_barrier
; #define PG8_STAGE(bufoff, gbase, voff) do { _Pragma("unroll") for (int _i = 0; _i < 2; ++_i) \
;         __builtin_amdgcn_global_load_lds((const unsigned*)((const char*)(gbase) + (voff)[_i]), (LAS unsigned*)(lds + (bufoff) + ldsw + _i * 8192), 16, 0, 0); } while (0)
; #define PG8_LDA(dst, b, h) do { _Pragma("unroll") for (int m = 0; m < 4; ++m) _Pragma("unroll") for (int k = 0; k < 2; ++k) dst[m][k] = *(const LAS bf16x8*)(lds + PG8_SA(b, h) + aoff + m * 2048 + k * 1024); } while (0)
; #define PG8_LDB(dst, b, h) do { _Pragma("unroll") for (int n = 0; n < 2; ++n) _Pragma("unroll") for (int k = 0; k < 2; ++k) dst[n][k] = *(const LAS bf16x8*)(lds + PG8_SB(b, h) + boff + n * 2048 + k * 1024); } while (0)
; #define PG8_MMA(ai, bj, At, Bt) do { __builtin_amdgcn_s_setprio(1); _Pragma("unroll") for (int m = 0; m < 4; ++m) _Pragma("unroll") for (int n = 0; n < 2; ++n) _Pragma("unroll") for (int k = 0; k < 2; ++k) \
;         acc[ai][bj][m][n] = __builtin_amdgcn_mfma_f32_16x16x32_bf16(Bt[n][k], At[m][k], acc[ai][bj][m][n], 0, 0, 0); __builtin_amdgcn_s_setprio(0); } while (0)
; #define PG8_WAIT_V(n) asm volatile("s_waitcnt vmcnt(" #n ")" ::: "memory")
; #define PG8_WAIT_L(n) asm volatile("s_waitcnt lgkmcnt(" #n ")" ::: "memory")
; #define PG8_BAR __builtin_amdgcn_s_barrier()
; #define PG8_SCHED __builtin_amdgcn_sched_barrier(0)
; template <class Epi, class Sched, bool ATILE = false>
; __device__ __forceinline__ void gemm_phase(LAS unsigned char* lds, const Gemm g, const Sched& S, const Epi& E) {
;     ...
;             PG8_WAIT_V(6); PG8_BAR; PG8_MMA(1, 1, At, B1); PG8_BAR;
;             PG8_LDB(B0, 1, 0); PG8_SCHED; PG8_LDA(At, 1, 0); PG8_STAGE(PG8_SA(0, 1), a2 + hstepA, voffA);
;             PG8_WAIT_L(8); PG8_BAR; PG8_WAIT_L(0); PG8_MMA(0, 0, At, B0); PG8_BAR; PG8_SCHED;
;             PG8_LDB(B1, 1, 1); PG8_STAGE(PG8_SB(1, 0), b3, voffB);
;             PG8_BAR; PG8_WAIT_L(0); PG8_MMA(0, 1, At, B1); PG8_BAR;
	s_setprio 1
	v_mfma_f32_16x16x32_bf16 v[60:63], v[224:227], v[192:195], v[60:63]
	v_mfma_f32_16x16x32_bf16 v[52:55], v[232:235], v[192:195], v[52:55]
	v_mfma_f32_16x16x32_bf16 v[44:47], v[224:227], v[200:203], v[44:47]
	v_mfma_f32_16x16x32_bf16 v[36:39], v[232:235], v[200:203], v[36:39]
	v_mfma_f32_16x16x32_bf16 v[28:31], v[224:227], v[208:211], v[28:31]
	v_mfma_f32_16x16x32_bf16 v[20:23], v[232:235], v[208:211], v[20:23]
	v_mfma_f32_16x16x32_bf16 v[12:15], v[224:227], v[216:219], v[12:15]
	v_mfma_f32_16x16x32_bf16 v[0:3], v[232:235], v[216:219], v[0:3]
	v_mfma_f32_16x16x32_bf16 v[60:63], v[228:231], v[196:199], v[60:63]
	v_mfma_f32_16x16x32_bf16 v[52:55], v[236:239], v[196:199], v[52:55]
	v_mfma_f32_16x16x32_bf16 v[44:47], v[228:231], v[204:207], v[44:47]
	v_mfma_f32_16x16x32_bf16 v[36:39], v[236:239], v[204:207], v[36:39]
	v_mfma_f32_16x16x32_bf16 v[28:31], v[228:231], v[212:215], v[28:31]
	v_mfma_f32_16x16x32_bf16 v[20:23], v[236:239], v[212:215], v[20:23]
	v_mfma_f32_16x16x32_bf16 v[12:15], v[228:231], v[220:223], v[12:15]
	v_mfma_f32_16x16x32_bf16 v[0:3], v[236:239], v[220:223], v[0:3]
	s_setprio 0
	s_barrier
	s_add_i32 s35, 0, 0x18000
	v_add_u32_e32 v172, s35, v157
	ds_read_b128 v[176:179], v172
	ds_read_b128 v[180:183], v172 offset:1024
	ds_read_b128 v[184:187], v172 offset:2048
	ds_read_b128 v[188:191], v172 offset:3072
	s_add_u32 s10, s10, 0x80000
	s_addc_u32 s11, s11, 0
	s_mov_b32 m0, s39
	ds_read_b128 v[192:195], v159 offset:32768
	ds_read_b128 v[196:199], v159 offset:33792
	ds_read_b128 v[200:203], v159 offset:34816
	ds_read_b128 v[204:207], v159 offset:35840
	ds_read_b128 v[208:211], v159 offset:36864
	ds_read_b128 v[212:215], v159 offset:37888
	ds_read_b128 v[216:219], v159 offset:38912
	ds_read_b128 v[220:223], v159 offset:39936
	global_load_lds_dwordx4 v128, s[10:11]
	s_mov_b32 m0, s40
	s_nop 0
	global_load_lds_dwordx4 v132, s[10:11]
	s_waitcnt lgkmcnt(8)
	s_barrier
	s_waitcnt lgkmcnt(0)
	s_setprio 1
	s_waitcnt lgkmcnt(0)
	v_mfma_f32_16x16x32_bf16 v[120:123], v[176:179], v[192:195], v[120:123]
	v_mfma_f32_16x16x32_bf16 v[112:115], v[184:187], v[192:195], v[112:115]
	v_mfma_f32_16x16x32_bf16 v[104:107], v[176:179], v[200:203], v[104:107]
	v_mfma_f32_16x16x32_bf16 v[96:99], v[184:187], v[200:203], v[96:99]
	v_mfma_f32_16x16x32_bf16 v[88:91], v[176:179], v[208:211], v[88:91]
	v_mfma_f32_16x16x32_bf16 v[80:83], v[184:187], v[208:211], v[80:83]
	v_mfma_f32_16x16x32_bf16 v[72:75], v[176:179], v[216:219], v[72:75]
	v_mfma_f32_16x16x32_bf16 v[64:67], v[184:187], v[216:219], v[64:67]
	v_mfma_f32_16x16x32_bf16 v[120:123], v[180:183], v[196:199], v[120:123]
	v_mfma_f32_16x16x32_bf16 v[112:115], v[188:191], v[196:199], v[112:115]
	v_mfma_f32_16x16x32_bf16 v[104:107], v[180:183], v[204:207], v[104:107]
	v_mfma_f32_16x16x32_bf16 v[96:99], v[188:191], v[204:207], v[96:99]
	v_mfma_f32_16x16x32_bf16 v[88:91], v[180:183], v[212:215], v[88:91]
	v_mfma_f32_16x16x32_bf16 v[80:83], v[188:191], v[212:215], v[80:83]
	v_mfma_f32_16x16x32_bf16 v[72:75], v[180:183], v[220:223], v[72:75]
	v_mfma_f32_16x16x32_bf16 v[64:67], v[188:191], v[220:223], v[64:67]
	s_setprio 0
	s_barrier
	s_add_i32 s10, 0, 0x1c000
	s_add_i32 s11, s35, s36
	v_add_u32_e32 v172, s10, v157
	s_mov_b32 m0, s11
	ds_read_b128 v[224:227], v172
	ds_read_b128 v[228:231], v172 offset:1024
	ds_read_b128 v[232:235], v172 offset:2048
	ds_read_b128 v[236:239], v172 offset:3072
	global_load_lds_dwordx4 v130, s[98:99]
	s_add_i32 m0, s11, 0x2000
	s_nop 0
	global_load_lds_dwordx4 v134, s[98:99]
	s_barrier
; #define PG8_STAGE(bufoff, gbase, voff) do { _Pragma("unroll") for (int _i = 0; _i < 2; ++_i) \
;         __builtin_amdgcn_global_load_lds((const unsigned*)((const char*)(gbase) + (voff)[_i]), (LAS unsigned*)(lds + (bufoff) + ldsw + _i * 8192), 16, 0, 0); } while (0)
; #define PG8_LDA(dst, b, h) do { _Pragma("unroll") for (int m = 0; m < 4; ++m) _Pragma("unroll") for (int k = 0; k < 2; ++k) dst[m][k] = *(const LAS bf16x8*)(lds + PG8_SA(b, h) + aoff + m * 2048 + k * 1024); } while (0)
; #define PG8_MMA(ai, bj, At, Bt) do { __builtin_amdgcn_s_setprio(1); _Pragma("unroll") for (int m = 0; m < 4; ++m) _Pragma("unroll") for (int n = 0; n < 2; ++n) _Pragma("unroll") for (int k = 0; k < 2; ++k) \
;         acc[ai][bj][m][n] = __builtin_amdgcn_mfma_f32_16x16x32_bf16(Bt[n][k], At[m][k], acc[ai][bj][m][n], 0, 0, 0); __builtin_amdgcn_s_setprio(0); } while (0)
; #define PG8_WAIT_V(n) asm volatile("s_waitcnt vmcnt(" #n ")" ::: "memory")
; #define PG8_WAIT_L(n) asm volatile("s_waitcnt lgkmcnt(" #n ")" ::: "memory")
; #define PG8_BAR __builtin_amdgcn_s_barrier()
; #define PG8_SCHED __builtin_amdgcn_sched_barrier(0)
; template <class Epi, class Sched, bool ATILE = false>
; __device__ __forceinline__ void gemm_phase(LAS unsigned char* lds, const Gemm g, const Sched& S, const Epi& E) {
;     ...
;             PG8_BAR; PG8_WAIT_L(0); PG8_MMA(0, 1, At, B1); PG8_BAR;
;             PG8_LDA(At, 1, 1); PG8_STAGE(PG8_SA(1, 0), a3, voffA);
;             PG8_BAR; PG8_WAIT_L(0); PG8_MMA(1, 0, At, B0); PG8_BAR; PG8_SCHED;
;             PG8_STAGE(PG8_SB(1, 1), b3 + hstepB, voffB);
;             PG8_WAIT_V(6); PG8_BAR; PG8_MMA(1, 1, At, B1); PG8_BAR;
;         }
;         E(acc, cur, wr, wc, fr, fq);
;         if (!has_next) break;
	s_waitcnt lgkmcnt(0)
	s_setprio 1
	s_waitcnt lgkmcnt(0)
	v_mfma_f32_16x16x32_bf16 v[124:127], v[224:227], v[192:195], v[124:127]
	v_mfma_f32_16x16x32_bf16 v[116:119], v[232:235], v[192:195], v[116:119]
	v_mfma_f32_16x16x32_bf16 v[108:111], v[224:227], v[200:203], v[108:111]
	v_mfma_f32_16x16x32_bf16 v[100:103], v[232:235], v[200:203], v[100:103]
	v_mfma_f32_16x16x32_bf16 v[92:95], v[224:227], v[208:211], v[92:95]
	v_mfma_f32_16x16x32_bf16 v[84:87], v[232:235], v[208:211], v[84:87]
	v_mfma_f32_16x16x32_bf16 v[76:79], v[224:227], v[216:219], v[76:79]
	v_mfma_f32_16x16x32_bf16 v[68:71], v[232:235], v[216:219], v[68:71]
	v_mfma_f32_16x16x32_bf16 v[124:127], v[228:231], v[196:199], v[124:127]
	v_mfma_f32_16x16x32_bf16 v[116:119], v[236:239], v[196:199], v[116:119]
	v_mfma_f32_16x16x32_bf16 v[108:111], v[228:231], v[204:207], v[108:111]
	v_mfma_f32_16x16x32_bf16 v[100:103], v[236:239], v[204:207], v[100:103]
	v_mfma_f32_16x16x32_bf16 v[92:95], v[228:231], v[212:215], v[92:95]
	v_mfma_f32_16x16x32_bf16 v[84:87], v[236:239], v[212:215], v[84:87]
	v_mfma_f32_16x16x32_bf16 v[76:79], v[228:231], v[220:223], v[76:79]
	v_mfma_f32_16x16x32_bf16 v[68:71], v[236:239], v[220:223], v[68:71]
	s_setprio 0
	s_barrier
	s_mov_b32 m0, s43
	ds_read_b128 v[192:195], v159 offset:49152
	ds_read_b128 v[196:199], v159 offset:50176
	ds_read_b128 v[200:203], v159 offset:51200
	ds_read_b128 v[204:207], v159 offset:52224
	ds_read_b128 v[208:211], v159 offset:53248
	ds_read_b128 v[212:215], v159 offset:54272
	ds_read_b128 v[216:219], v159 offset:55296
	ds_read_b128 v[220:223], v159 offset:56320
	global_load_lds_dwordx4 v128, s[100:101]
	s_mov_b32 m0, s44
	s_nop 0
	global_load_lds_dwordx4 v132, s[100:101]
	s_barrier
	s_waitcnt lgkmcnt(0)
	s_setprio 1
	s_waitcnt lgkmcnt(0)
	v_mfma_f32_16x16x32_bf16 v[56:59], v[176:179], v[192:195], v[56:59]
	v_mfma_f32_16x16x32_bf16 v[48:51], v[184:187], v[192:195], v[48:51]
	v_mfma_f32_16x16x32_bf16 v[40:43], v[176:179], v[200:203], v[40:43]
	v_mfma_f32_16x16x32_bf16 v[32:35], v[184:187], v[200:203], v[32:35]
	v_mfma_f32_16x16x32_bf16 v[24:27], v[176:179], v[208:211], v[24:27]
	v_mfma_f32_16x16x32_bf16 v[16:19], v[184:187], v[208:211], v[16:19]
	v_mfma_f32_16x16x32_bf16 v[8:11], v[176:179], v[216:219], v[8:11]
	v_mfma_f32_16x16x32_bf16 v[4:7], v[184:187], v[216:219], v[4:7]
	v_mfma_f32_16x16x32_bf16 v[56:59], v[180:183], v[196:199], v[56:59]
	v_mfma_f32_16x16x32_bf16 v[48:51], v[188:191], v[196:199], v[48:51]
	v_mfma_f32_16x16x32_bf16 v[40:43], v[180:183], v[204:207], v[40:43]
	v_mfma_f32_16x16x32_bf16 v[32:35], v[188:191], v[204:207], v[32:35]
	v_mfma_f32_16x16x32_bf16 v[24:27], v[180:183], v[212:215], v[24:27]
	v_mfma_f32_16x16x32_bf16 v[16:19], v[188:191], v[212:215], v[16:19]
	v_mfma_f32_16x16x32_bf16 v[8:11], v[180:183], v[220:223], v[8:11]
	v_mfma_f32_16x16x32_bf16 v[4:7], v[188:191], v[220:223], v[4:7]
	s_setprio 0
	s_barrier
	s_add_u32 s8, s8, 0x80080
	s_addc_u32 s9, s9, 0
	s_add_i32 s10, s10, s36
	s_mov_b32 m0, s10
	s_nop 0
	global_load_lds_dwordx4 v130, s[8:9]
	s_add_i32 m0, s10, 0x2000
	s_nop 0
	global_load_lds_dwordx4 v134, s[8:9]
	s_waitcnt vmcnt(6)
	s_barrier
	s_setprio 1
	v_mfma_f32_16x16x32_bf16 v[60:63], v[224:227], v[192:195], v[60:63]
	v_mfma_f32_16x16x32_bf16 v[52:55], v[232:235], v[192:195], v[52:55]
	v_mfma_f32_16x16x32_bf16 v[44:47], v[224:227], v[200:203], v[44:47]
	v_mfma_f32_16x16x32_bf16 v[36:39], v[232:235], v[200:203], v[36:39]
	v_mfma_f32_16x16x32_bf16 v[28:31], v[224:227], v[208:211], v[28:31]
	v_mfma_f32_16x16x32_bf16 v[20:23], v[232:235], v[208:211], v[20:23]
	v_mfma_f32_16x16x32_bf16 v[12:15], v[224:227], v[216:219], v[12:15]
	v_mfma_f32_16x16x32_bf16 v[0:3], v[232:235], v[216:219], v[0:3]
	v_mfma_f32_16x16x32_bf16 v[60:63], v[228:231], v[196:199], v[60:63]
	v_mfma_f32_16x16x32_bf16 v[52:55], v[236:239], v[196:199], v[52:55]
	v_mfma_f32_16x16x32_bf16 v[44:47], v[228:231], v[204:207], v[44:47]
	v_mfma_f32_16x16x32_bf16 v[36:39], v[236:239], v[204:207], v[36:39]
	v_mfma_f32_16x16x32_bf16 v[28:31], v[228:231], v[212:215], v[28:31]
	v_mfma_f32_16x16x32_bf16 v[20:23], v[236:239], v[212:215], v[20:23]
	v_mfma_f32_16x16x32_bf16 v[12:15], v[228:231], v[220:223], v[12:15]
	v_mfma_f32_16x16x32_bf16 v[0:3], v[236:239], v[220:223], v[0:3]
	s_setprio 0
	s_barrier
	s_add_u32 s6, s6, 0x100
	s_addc_u32 s7, s7, 0
	s_add_u32 s25, s25, 0x100
	s_addc_u32 s27, s27, 0
	s_cmp_ge_i32 s34, s12
	s_mov_b32 s8, s34
	s_cbranch_scc0 .LBB0_1812
	s_branch .LBB0_1803

; #define LAS __attribute__((address_space(3)))
; __global__ void __launch_bounds__(512, 2) fwd_megakernel(Params p) {
;     extern __shared__ __attribute__((aligned(16))) unsigned char lds_raw[];
;     LAS unsigned char* lds = (LAS unsigned char*)lds_raw;
	.amdhsa_kernel _Z14fwd_megakernel6Params
		.amdhsa_group_segment_fixed_size 0
		.amdhsa_private_segment_fixed_size 0
		.amdhsa_kernarg_size 552
		.amdhsa_user_sgpr_count 2
		.amdhsa_user_sgpr_dispatch_ptr 0
		.amdhsa_user_sgpr_queue_ptr 0
		.amdhsa_user_sgpr_kernarg_segment_ptr 1
		.amdhsa_user_sgpr_dispatch_id 0
		.amdhsa_user_sgpr_kernarg_preload_length 0
		.amdhsa_user_sgpr_kernarg_preload_offset 0
		.amdhsa_user_sgpr_private_segment_size 0
		.amdhsa_uses_dynamic_stack 0
		.amdhsa_enable_private_segment 0
		.amdhsa_system_sgpr_workgroup_id_x 1
		.amdhsa_system_sgpr_workgroup_id_y 0
		.amdhsa_system_sgpr_workgroup_id_z 0
		.amdhsa_system_sgpr_workgroup_info 0
		.amdhsa_system_vgpr_workitem_id 2
		.amdhsa_next_free_vgpr 256
		.amdhsa_next_free_sgpr 102
		.amdhsa_accum_offset 256
		.amdhsa_reserve_vcc 1
		.amdhsa_float_round_mode_32 0
		.amdhsa_float_round_mode_16_64 0
		.amdhsa_float_denorm_mode_32 3
		.amdhsa_float_denorm_mode_16_64 3
		.amdhsa_dx10_clamp 1
		.amdhsa_ieee_mode 1
		.amdhsa_fp16_overflow 0
		.amdhsa_tg_split 0
		.amdhsa_exception_fp_ieee_invalid_op 0
		.amdhsa_exception_fp_denorm_src 0
		.amdhsa_exception_fp_ieee_div_zero 0
		.amdhsa_exception_fp_ieee_overflow 0
		.amdhsa_exception_fp_ieee_underflow 0
		.amdhsa_exception_fp_ieee_inexact 0
		.amdhsa_exception_int_div_zero 0
	.end_amdhsa_kernel

; #define LAS __attribute__((address_space(3)))
; __global__ void __launch_bounds__(512, 2) fwd_megakernel(Params p) {
;     extern __shared__ __attribute__((aligned(16))) unsigned char lds_raw[];
;     LAS unsigned char* lds = (LAS unsigned char*)lds_raw;
amdhsa.kernels:
  - .agpr_count:     0
    .args:
      - .offset:         0
        .size:           296
        .value_kind:     by_value
      - .offset:         296
        .size:           4
        .value_kind:     hidden_block_count_x
      - .offset:         300
        .size:           4
        .value_kind:     hidden_block_count_y
      - .offset:         304
        .size:           4
        .value_kind:     hidden_block_count_z
      - .offset:         308
        .size:           2
        .value_kind:     hidden_group_size_x
      - .offset:         310
        .size:           2
        .value_kind:     hidden_group_size_y
      - .offset:         312
        .size:           2
        .value_kind:     hidden_group_size_z
      - .offset:         314
        .size:           2
        .value_kind:     hidden_remainder_x
      - .offset:         316
        .size:           2
        .value_kind:     hidden_remainder_y
      - .offset:         318
        .size:           2
        .value_kind:     hidden_remainder_z
      - .offset:         336
        .size:           8
        .value_kind:     hidden_global_offset_x
      - .offset:         344
        .size:           8
        .value_kind:     hidden_global_offset_y
      - .offset:         352
        .size:           8
        .value_kind:     hidden_global_offset_z
      - .offset:         360
        .size:           2
        .value_kind:     hidden_grid_dims
      - .offset:         384
        .size:           8
        .value_kind:     hidden_multigrid_sync_arg
      - .offset:         416
        .size:           4
        .value_kind:     hidden_dynamic_lds_size
    .group_segment_fixed_size: 0
    .kernarg_segment_align: 8
    .kernarg_segment_size: 552
    .language:       OpenCL C
    .language_version:
      - 2
      - 0
    .max_flat_workgroup_size: 512
    .name:           _Z14fwd_megakernel6Params
    .private_segment_fixed_size: 0
    .sgpr_count:     108
    .sgpr_spill_count: 86
    .symbol:         _Z14fwd_megakernel6Params.kd
    .uniform_work_group_size: 1
    .uses_dynamic_stack: false
    .vgpr_count:     256
    .vgpr_spill_count: 0
    .wavefront_size: 64
